# in-projection MG/GLU/Q epilogues hand-written: rcp+Newton+div_fixup sigmoid in f32, LDS transpose, full-row stores (incl. half-tile tail)
# speedup vs baseline: 1.0562x; 1.0128x over previous
; DI float sigmoidf_(float x) { return 1.f / (1.f + __expf(-x)); }
; template <int WM>
; DI void inproj_tile(const Params& p, char* smem, const int m0, const int n0) {
;     ...
;   } else if (fw < 4352) {
; #pragma unroll
;     for (int i = 0; i < WM; ++i)
; #pragma unroll
;       for (int j = 0; j < 2; ++j)
; #pragma unroll
;         for (int q4 = 0; q4 < 4; ++q4) {
;           const int f = fw - 2304 + i * 32 + q4 * 8 + hh * 4;
;           const size_t t = tb + j * 32;
;           uint2 o;
;           o.x = pack2(sigmoidf_(acc[i][j][q4 * 4 + 0]), sigmoidf_(acc[i][j][q4 * 4 + 1]));
;           o.y = pack2(sigmoidf_(acc[i][j][q4 * 4 + 2]), sigmoidf_(acc[i][j][q4 * 4 + 3]));
;           *(uint2*)(MG + t * 2048 + f) = o;
;         }
.LBB0_174:
	s_andn2_saveexec_b64 s[22:23], s[22:23]
	s_cbranch_execz .LBB0_176
	s_waitcnt vmcnt(0)
	v_mbcnt_lo_u32_b32 v143, -1, 0
	v_mbcnt_hi_u32_b32 v143, -1, v143
	v_lshrrev_b32_e32 v132, 6, v211
	v_mul_u32_u24_e32 v132, 17408, v132
	v_and_b32_e32 v133, 31, v143
	v_lshrrev_b32_e32 v134, 5, v143
	v_mul_u32_u24_e32 v133, 272, v133
	v_lshl_add_u32 v133, v134, 3, v133
	v_add3_u32 v140, v133, v132, 64
	v_lshrrev_b32_e32 v135, 4, v143
	v_and_b32_e32 v136, 15, v143
	v_mul_u32_u24_e32 v137, 272, v135
	v_lshl_add_u32 v137, v136, 4, v137
	v_add3_u32 v141, v137, v132, 64
	v_and_b32_e32 v138, 0xffffffe0, v129
	v_add_u32_e32 v138, v138, v135
	v_lshlrev_b32_e32 v138, 12, v138
	v_add_u32_e32 v139, 4294964992, v131
	v_lshl_add_u32 v138, v139, 1, v138
	v_lshl_add_u32 v142, v136, 4, v138
	s_mov_b32 s12, 0xbfb8aa3b
	v_pk_mul_f32 v[132:133], v[112:113], s[12:13] op_sel_hi:[1,0]
	v_pk_mul_f32 v[134:135], v[114:115], s[12:13] op_sel_hi:[1,0]
	v_exp_f32_e32 v132, v132
	v_exp_f32_e32 v133, v133
	v_exp_f32_e32 v134, v134
	v_exp_f32_e32 v135, v135
	v_pk_add_f32 v[132:133], v[132:133], 1.0 op_sel_hi:[1,0]
	v_pk_add_f32 v[134:135], v[134:135], 1.0 op_sel_hi:[1,0]
	v_rcp_f32_e32 v136, v132
	v_rcp_f32_e32 v137, v133
	v_rcp_f32_e32 v138, v134
	v_rcp_f32_e32 v139, v135
	v_pk_fma_f32 v[112:113], v[132:133], v[136:137], 1.0 op_sel_hi:[1,1,0] neg_lo:[1,0,0] neg_hi:[1,0,0]
	v_pk_fma_f32 v[114:115], v[134:135], v[138:139], 1.0 op_sel_hi:[1,1,0] neg_lo:[1,0,0] neg_hi:[1,0,0]
	v_pk_fma_f32 v[136:137], v[112:113], v[136:137], v[136:137]
	v_pk_fma_f32 v[138:139], v[114:115], v[138:139], v[138:139]
	v_div_fixup_f32 v136, v136, v132, 1.0
	v_div_fixup_f32 v137, v137, v133, 1.0
	v_div_fixup_f32 v138, v138, v134, 1.0
	v_div_fixup_f32 v139, v139, v135, 1.0
	v_cvt_pk_bf16_f32 v112, v136, v137
	v_cvt_pk_bf16_f32 v113, v138, v139
	ds_write_b64 v140, v[112:113] offset:0
	v_pk_mul_f32 v[132:133], v[116:117], s[12:13] op_sel_hi:[1,0]
	v_pk_mul_f32 v[134:135], v[118:119], s[12:13] op_sel_hi:[1,0]
	v_exp_f32_e32 v132, v132
	v_exp_f32_e32 v133, v133
	v_exp_f32_e32 v134, v134
	v_exp_f32_e32 v135, v135
	v_pk_add_f32 v[132:133], v[132:133], 1.0 op_sel_hi:[1,0]
	v_pk_add_f32 v[134:135], v[134:135], 1.0 op_sel_hi:[1,0]
	v_rcp_f32_e32 v136, v132
	v_rcp_f32_e32 v137, v133
	v_rcp_f32_e32 v138, v134
	v_rcp_f32_e32 v139, v135
	v_pk_fma_f32 v[116:117], v[132:133], v[136:137], 1.0 op_sel_hi:[1,1,0] neg_lo:[1,0,0] neg_hi:[1,0,0]
	v_pk_fma_f32 v[118:119], v[134:135], v[138:139], 1.0 op_sel_hi:[1,1,0] neg_lo:[1,0,0] neg_hi:[1,0,0]
	v_pk_fma_f32 v[136:137], v[116:117], v[136:137], v[136:137]
	v_pk_fma_f32 v[138:139], v[118:119], v[138:139], v[138:139]
	v_div_fixup_f32 v136, v136, v132, 1.0
	v_div_fixup_f32 v137, v137, v133, 1.0
	v_div_fixup_f32 v138, v138, v134, 1.0
	v_div_fixup_f32 v139, v139, v135, 1.0
	v_cvt_pk_bf16_f32 v116, v136, v137
	v_cvt_pk_bf16_f32 v117, v138, v139
	ds_write_b64 v140, v[116:117] offset:16
	v_pk_mul_f32 v[132:133], v[120:121], s[12:13] op_sel_hi:[1,0]
	v_pk_mul_f32 v[134:135], v[122:123], s[12:13] op_sel_hi:[1,0]
	v_exp_f32_e32 v132, v132
	v_exp_f32_e32 v133, v133
	v_exp_f32_e32 v134, v134
	v_exp_f32_e32 v135, v135
	v_pk_add_f32 v[132:133], v[132:133], 1.0 op_sel_hi:[1,0]
	v_pk_add_f32 v[134:135], v[134:135], 1.0 op_sel_hi:[1,0]
	v_rcp_f32_e32 v136, v132
	v_rcp_f32_e32 v137, v133
	v_rcp_f32_e32 v138, v134
	v_rcp_f32_e32 v139, v135
	v_pk_fma_f32 v[120:121], v[132:133], v[136:137], 1.0 op_sel_hi:[1,1,0] neg_lo:[1,0,0] neg_hi:[1,0,0]
	v_pk_fma_f32 v[122:123], v[134:135], v[138:139], 1.0 op_sel_hi:[1,1,0] neg_lo:[1,0,0] neg_hi:[1,0,0]
	v_pk_fma_f32 v[136:137], v[120:121], v[136:137], v[136:137]
	v_pk_fma_f32 v[138:139], v[122:123], v[138:139], v[138:139]
	v_div_fixup_f32 v136, v136, v132, 1.0
	v_div_fixup_f32 v137, v137, v133, 1.0
	v_div_fixup_f32 v138, v138, v134, 1.0
	v_div_fixup_f32 v139, v139, v135, 1.0
	v_cvt_pk_bf16_f32 v120, v136, v137
	v_cvt_pk_bf16_f32 v121, v138, v139
	ds_write_b64 v140, v[120:121] offset:32
	v_pk_mul_f32 v[132:133], v[124:125], s[12:13] op_sel_hi:[1,0]
	v_pk_mul_f32 v[134:135], v[126:127], s[12:13] op_sel_hi:[1,0]
	v_exp_f32_e32 v132, v132
	v_exp_f32_e32 v133, v133
	v_exp_f32_e32 v134, v134
	v_exp_f32_e32 v135, v135
	v_pk_add_f32 v[132:133], v[132:133], 1.0 op_sel_hi:[1,0]
	v_pk_add_f32 v[134:135], v[134:135], 1.0 op_sel_hi:[1,0]
	v_rcp_f32_e32 v136, v132
	v_rcp_f32_e32 v137, v133
	v_rcp_f32_e32 v138, v134
	v_rcp_f32_e32 v139, v135
	v_pk_fma_f32 v[124:125], v[132:133], v[136:137], 1.0 op_sel_hi:[1,1,0] neg_lo:[1,0,0] neg_hi:[1,0,0]
	v_pk_fma_f32 v[126:127], v[134:135], v[138:139], 1.0 op_sel_hi:[1,1,0] neg_lo:[1,0,0] neg_hi:[1,0,0]
	v_pk_fma_f32 v[136:137], v[124:125], v[136:137], v[136:137]
	v_pk_fma_f32 v[138:139], v[126:127], v[138:139], v[138:139]
	v_div_fixup_f32 v136, v136, v132, 1.0
	v_div_fixup_f32 v137, v137, v133, 1.0
	v_div_fixup_f32 v138, v138, v134, 1.0
	v_div_fixup_f32 v139, v139, v135, 1.0
	v_cvt_pk_bf16_f32 v124, v136, v137
	v_cvt_pk_bf16_f32 v125, v138, v139
	ds_write_b64 v140, v[124:125] offset:48
	v_pk_mul_f32 v[132:133], v[80:81], s[12:13] op_sel_hi:[1,0]
	v_pk_mul_f32 v[134:135], v[82:83], s[12:13] op_sel_hi:[1,0]
	v_exp_f32_e32 v132, v132
	v_exp_f32_e32 v133, v133
	v_exp_f32_e32 v134, v134
	v_exp_f32_e32 v135, v135
	v_pk_add_f32 v[132:133], v[132:133], 1.0 op_sel_hi:[1,0]
	v_pk_add_f32 v[134:135], v[134:135], 1.0 op_sel_hi:[1,0]
	v_rcp_f32_e32 v136, v132
	v_rcp_f32_e32 v137, v133
	v_rcp_f32_e32 v138, v134
	v_rcp_f32_e32 v139, v135
	v_pk_fma_f32 v[80:81], v[132:133], v[136:137], 1.0 op_sel_hi:[1,1,0] neg_lo:[1,0,0] neg_hi:[1,0,0]
	v_pk_fma_f32 v[82:83], v[134:135], v[138:139], 1.0 op_sel_hi:[1,1,0] neg_lo:[1,0,0] neg_hi:[1,0,0]
; DI float sigmoidf_(float x) { return 1.f / (1.f + __expf(-x)); }
; template <int WM>
; DI void inproj_tile(const Params& p, char* smem, const int m0, const int n0) {
;     ...
;   } else if (fw < 4352) {
; #pragma unroll
;     for (int i = 0; i < WM; ++i)
; #pragma unroll
;       for (int j = 0; j < 2; ++j)
; #pragma unroll
;         for (int q4 = 0; q4 < 4; ++q4) {
;           const int f = fw - 2304 + i * 32 + q4 * 8 + hh * 4;
;           const size_t t = tb + j * 32;
;           uint2 o;
;           o.x = pack2(sigmoidf_(acc[i][j][q4 * 4 + 0]), sigmoidf_(acc[i][j][q4 * 4 + 1]));
;           o.y = pack2(sigmoidf_(acc[i][j][q4 * 4 + 2]), sigmoidf_(acc[i][j][q4 * 4 + 3]));
;           *(uint2*)(MG + t * 2048 + f) = o;
;         }
	v_pk_fma_f32 v[136:137], v[80:81], v[136:137], v[136:137]
	v_pk_fma_f32 v[138:139], v[82:83], v[138:139], v[138:139]
	v_div_fixup_f32 v136, v136, v132, 1.0
	v_div_fixup_f32 v137, v137, v133, 1.0
	v_div_fixup_f32 v138, v138, v134, 1.0
	v_div_fixup_f32 v139, v139, v135, 1.0
	v_cvt_pk_bf16_f32 v80, v136, v137
	v_cvt_pk_bf16_f32 v81, v138, v139
	ds_write_b64 v140, v[80:81] offset:64
	v_pk_mul_f32 v[132:133], v[84:85], s[12:13] op_sel_hi:[1,0]
	v_pk_mul_f32 v[134:135], v[86:87], s[12:13] op_sel_hi:[1,0]
	v_exp_f32_e32 v132, v132
	v_exp_f32_e32 v133, v133
	v_exp_f32_e32 v134, v134
	v_exp_f32_e32 v135, v135
	v_pk_add_f32 v[132:133], v[132:133], 1.0 op_sel_hi:[1,0]
	v_pk_add_f32 v[134:135], v[134:135], 1.0 op_sel_hi:[1,0]
	v_rcp_f32_e32 v136, v132
	v_rcp_f32_e32 v137, v133
	v_rcp_f32_e32 v138, v134
	v_rcp_f32_e32 v139, v135
	v_pk_fma_f32 v[84:85], v[132:133], v[136:137], 1.0 op_sel_hi:[1,1,0] neg_lo:[1,0,0] neg_hi:[1,0,0]
	v_pk_fma_f32 v[86:87], v[134:135], v[138:139], 1.0 op_sel_hi:[1,1,0] neg_lo:[1,0,0] neg_hi:[1,0,0]
	v_pk_fma_f32 v[136:137], v[84:85], v[136:137], v[136:137]
	v_pk_fma_f32 v[138:139], v[86:87], v[138:139], v[138:139]
	v_div_fixup_f32 v136, v136, v132, 1.0
	v_div_fixup_f32 v137, v137, v133, 1.0
	v_div_fixup_f32 v138, v138, v134, 1.0
	v_div_fixup_f32 v139, v139, v135, 1.0
	v_cvt_pk_bf16_f32 v84, v136, v137
	v_cvt_pk_bf16_f32 v85, v138, v139
	ds_write_b64 v140, v[84:85] offset:80
	v_pk_mul_f32 v[132:133], v[88:89], s[12:13] op_sel_hi:[1,0]
	v_pk_mul_f32 v[134:135], v[90:91], s[12:13] op_sel_hi:[1,0]
	v_exp_f32_e32 v132, v132
	v_exp_f32_e32 v133, v133
	v_exp_f32_e32 v134, v134
	v_exp_f32_e32 v135, v135
	v_pk_add_f32 v[132:133], v[132:133], 1.0 op_sel_hi:[1,0]
	v_pk_add_f32 v[134:135], v[134:135], 1.0 op_sel_hi:[1,0]
	v_rcp_f32_e32 v136, v132
	v_rcp_f32_e32 v137, v133
	v_rcp_f32_e32 v138, v134
	v_rcp_f32_e32 v139, v135
	v_pk_fma_f32 v[88:89], v[132:133], v[136:137], 1.0 op_sel_hi:[1,1,0] neg_lo:[1,0,0] neg_hi:[1,0,0]
	v_pk_fma_f32 v[90:91], v[134:135], v[138:139], 1.0 op_sel_hi:[1,1,0] neg_lo:[1,0,0] neg_hi:[1,0,0]
	v_pk_fma_f32 v[136:137], v[88:89], v[136:137], v[136:137]
	v_pk_fma_f32 v[138:139], v[90:91], v[138:139], v[138:139]
	v_div_fixup_f32 v136, v136, v132, 1.0
	v_div_fixup_f32 v137, v137, v133, 1.0
	v_div_fixup_f32 v138, v138, v134, 1.0
	v_div_fixup_f32 v139, v139, v135, 1.0
	v_cvt_pk_bf16_f32 v88, v136, v137
	v_cvt_pk_bf16_f32 v89, v138, v139
	ds_write_b64 v140, v[88:89] offset:96
	v_pk_mul_f32 v[132:133], v[92:93], s[12:13] op_sel_hi:[1,0]
	v_pk_mul_f32 v[134:135], v[94:95], s[12:13] op_sel_hi:[1,0]
	v_exp_f32_e32 v132, v132
	v_exp_f32_e32 v133, v133
	v_exp_f32_e32 v134, v134
	v_exp_f32_e32 v135, v135
	v_pk_add_f32 v[132:133], v[132:133], 1.0 op_sel_hi:[1,0]
	v_pk_add_f32 v[134:135], v[134:135], 1.0 op_sel_hi:[1,0]
	v_rcp_f32_e32 v136, v132
	v_rcp_f32_e32 v137, v133
	v_rcp_f32_e32 v138, v134
	v_rcp_f32_e32 v139, v135
	v_pk_fma_f32 v[92:93], v[132:133], v[136:137], 1.0 op_sel_hi:[1,1,0] neg_lo:[1,0,0] neg_hi:[1,0,0]
	v_pk_fma_f32 v[94:95], v[134:135], v[138:139], 1.0 op_sel_hi:[1,1,0] neg_lo:[1,0,0] neg_hi:[1,0,0]
	v_pk_fma_f32 v[136:137], v[92:93], v[136:137], v[136:137]
	v_pk_fma_f32 v[138:139], v[94:95], v[138:139], v[138:139]
	v_div_fixup_f32 v136, v136, v132, 1.0
	v_div_fixup_f32 v137, v137, v133, 1.0
	v_div_fixup_f32 v138, v138, v134, 1.0
	v_div_fixup_f32 v139, v139, v135, 1.0
	v_cvt_pk_bf16_f32 v92, v136, v137
	v_cvt_pk_bf16_f32 v93, v138, v139
	ds_write_b64 v140, v[92:93] offset:112
	v_pk_mul_f32 v[132:133], v[48:49], s[12:13] op_sel_hi:[1,0]
	v_pk_mul_f32 v[134:135], v[50:51], s[12:13] op_sel_hi:[1,0]
	v_exp_f32_e32 v132, v132
	v_exp_f32_e32 v133, v133
	v_exp_f32_e32 v134, v134
	v_exp_f32_e32 v135, v135
	v_pk_add_f32 v[132:133], v[132:133], 1.0 op_sel_hi:[1,0]
	v_pk_add_f32 v[134:135], v[134:135], 1.0 op_sel_hi:[1,0]
	v_rcp_f32_e32 v136, v132
	v_rcp_f32_e32 v137, v133
	v_rcp_f32_e32 v138, v134
	v_rcp_f32_e32 v139, v135
	v_pk_fma_f32 v[48:49], v[132:133], v[136:137], 1.0 op_sel_hi:[1,1,0] neg_lo:[1,0,0] neg_hi:[1,0,0]
	v_pk_fma_f32 v[50:51], v[134:135], v[138:139], 1.0 op_sel_hi:[1,1,0] neg_lo:[1,0,0] neg_hi:[1,0,0]
	v_pk_fma_f32 v[136:137], v[48:49], v[136:137], v[136:137]
	v_pk_fma_f32 v[138:139], v[50:51], v[138:139], v[138:139]
	v_div_fixup_f32 v136, v136, v132, 1.0
	v_div_fixup_f32 v137, v137, v133, 1.0
	v_div_fixup_f32 v138, v138, v134, 1.0
	v_div_fixup_f32 v139, v139, v135, 1.0
	v_cvt_pk_bf16_f32 v48, v136, v137
	v_cvt_pk_bf16_f32 v49, v138, v139
	ds_write_b64 v140, v[48:49] offset:128
	v_pk_mul_f32 v[132:133], v[52:53], s[12:13] op_sel_hi:[1,0]
	v_pk_mul_f32 v[134:135], v[54:55], s[12:13] op_sel_hi:[1,0]
	v_exp_f32_e32 v132, v132
	v_exp_f32_e32 v133, v133
	v_exp_f32_e32 v134, v134
	v_exp_f32_e32 v135, v135
	v_pk_add_f32 v[132:133], v[132:133], 1.0 op_sel_hi:[1,0]
	v_pk_add_f32 v[134:135], v[134:135], 1.0 op_sel_hi:[1,0]
	v_rcp_f32_e32 v136, v132
	v_rcp_f32_e32 v137, v133
	v_rcp_f32_e32 v138, v134
	v_rcp_f32_e32 v139, v135
	v_pk_fma_f32 v[52:53], v[132:133], v[136:137], 1.0 op_sel_hi:[1,1,0] neg_lo:[1,0,0] neg_hi:[1,0,0]
	v_pk_fma_f32 v[54:55], v[134:135], v[138:139], 1.0 op_sel_hi:[1,1,0] neg_lo:[1,0,0] neg_hi:[1,0,0]
	v_pk_fma_f32 v[136:137], v[52:53], v[136:137], v[136:137]
	v_pk_fma_f32 v[138:139], v[54:55], v[138:139], v[138:139]
	v_div_fixup_f32 v136, v136, v132, 1.0
	v_div_fixup_f32 v137, v137, v133, 1.0
	v_div_fixup_f32 v138, v138, v134, 1.0
	v_div_fixup_f32 v139, v139, v135, 1.0
	v_cvt_pk_bf16_f32 v52, v136, v137
	v_cvt_pk_bf16_f32 v53, v138, v139
	ds_write_b64 v140, v[52:53] offset:144
	v_pk_mul_f32 v[132:133], v[56:57], s[12:13] op_sel_hi:[1,0]
	v_pk_mul_f32 v[134:135], v[58:59], s[12:13] op_sel_hi:[1,0]
; DI float sigmoidf_(float x) { return 1.f / (1.f + __expf(-x)); }
; template <int WM>
; DI void inproj_tile(const Params& p, char* smem, const int m0, const int n0) {
;     ...
;   } else if (fw < 4352) {
; #pragma unroll
;     for (int i = 0; i < WM; ++i)
; #pragma unroll
;       for (int j = 0; j < 2; ++j)
; #pragma unroll
;         for (int q4 = 0; q4 < 4; ++q4) {
;           const int f = fw - 2304 + i * 32 + q4 * 8 + hh * 4;
;           const size_t t = tb + j * 32;
;           uint2 o;
;           o.x = pack2(sigmoidf_(acc[i][j][q4 * 4 + 0]), sigmoidf_(acc[i][j][q4 * 4 + 1]));
;           o.y = pack2(sigmoidf_(acc[i][j][q4 * 4 + 2]), sigmoidf_(acc[i][j][q4 * 4 + 3]));
;           *(uint2*)(MG + t * 2048 + f) = o;
;         }
	v_exp_f32_e32 v132, v132
	v_exp_f32_e32 v133, v133
	v_exp_f32_e32 v134, v134
	v_exp_f32_e32 v135, v135
	v_pk_add_f32 v[132:133], v[132:133], 1.0 op_sel_hi:[1,0]
	v_pk_add_f32 v[134:135], v[134:135], 1.0 op_sel_hi:[1,0]
	v_rcp_f32_e32 v136, v132
	v_rcp_f32_e32 v137, v133
	v_rcp_f32_e32 v138, v134
	v_rcp_f32_e32 v139, v135
	v_pk_fma_f32 v[56:57], v[132:133], v[136:137], 1.0 op_sel_hi:[1,1,0] neg_lo:[1,0,0] neg_hi:[1,0,0]
	v_pk_fma_f32 v[58:59], v[134:135], v[138:139], 1.0 op_sel_hi:[1,1,0] neg_lo:[1,0,0] neg_hi:[1,0,0]
	v_pk_fma_f32 v[136:137], v[56:57], v[136:137], v[136:137]
	v_pk_fma_f32 v[138:139], v[58:59], v[138:139], v[138:139]
	v_div_fixup_f32 v136, v136, v132, 1.0
	v_div_fixup_f32 v137, v137, v133, 1.0
	v_div_fixup_f32 v138, v138, v134, 1.0
	v_div_fixup_f32 v139, v139, v135, 1.0
	v_cvt_pk_bf16_f32 v56, v136, v137
	v_cvt_pk_bf16_f32 v57, v138, v139
	ds_write_b64 v140, v[56:57] offset:160
	v_pk_mul_f32 v[132:133], v[60:61], s[12:13] op_sel_hi:[1,0]
	v_pk_mul_f32 v[134:135], v[62:63], s[12:13] op_sel_hi:[1,0]
	v_exp_f32_e32 v132, v132
	v_exp_f32_e32 v133, v133
	v_exp_f32_e32 v134, v134
	v_exp_f32_e32 v135, v135
	v_pk_add_f32 v[132:133], v[132:133], 1.0 op_sel_hi:[1,0]
	v_pk_add_f32 v[134:135], v[134:135], 1.0 op_sel_hi:[1,0]
	v_rcp_f32_e32 v136, v132
	v_rcp_f32_e32 v137, v133
	v_rcp_f32_e32 v138, v134
	v_rcp_f32_e32 v139, v135
	v_pk_fma_f32 v[60:61], v[132:133], v[136:137], 1.0 op_sel_hi:[1,1,0] neg_lo:[1,0,0] neg_hi:[1,0,0]
	v_pk_fma_f32 v[62:63], v[134:135], v[138:139], 1.0 op_sel_hi:[1,1,0] neg_lo:[1,0,0] neg_hi:[1,0,0]
	v_pk_fma_f32 v[136:137], v[60:61], v[136:137], v[136:137]
	v_pk_fma_f32 v[138:139], v[62:63], v[138:139], v[138:139]
	v_div_fixup_f32 v136, v136, v132, 1.0
	v_div_fixup_f32 v137, v137, v133, 1.0
	v_div_fixup_f32 v138, v138, v134, 1.0
	v_div_fixup_f32 v139, v139, v135, 1.0
	v_cvt_pk_bf16_f32 v60, v136, v137
	v_cvt_pk_bf16_f32 v61, v138, v139
	ds_write_b64 v140, v[60:61] offset:176
	v_pk_mul_f32 v[132:133], v[16:17], s[12:13] op_sel_hi:[1,0]
	v_pk_mul_f32 v[134:135], v[18:19], s[12:13] op_sel_hi:[1,0]
	v_exp_f32_e32 v132, v132
	v_exp_f32_e32 v133, v133
	v_exp_f32_e32 v134, v134
	v_exp_f32_e32 v135, v135
	v_pk_add_f32 v[132:133], v[132:133], 1.0 op_sel_hi:[1,0]
	v_pk_add_f32 v[134:135], v[134:135], 1.0 op_sel_hi:[1,0]
	v_rcp_f32_e32 v136, v132
	v_rcp_f32_e32 v137, v133
	v_rcp_f32_e32 v138, v134
	v_rcp_f32_e32 v139, v135
	v_pk_fma_f32 v[16:17], v[132:133], v[136:137], 1.0 op_sel_hi:[1,1,0] neg_lo:[1,0,0] neg_hi:[1,0,0]
	v_pk_fma_f32 v[18:19], v[134:135], v[138:139], 1.0 op_sel_hi:[1,1,0] neg_lo:[1,0,0] neg_hi:[1,0,0]
	v_pk_fma_f32 v[136:137], v[16:17], v[136:137], v[136:137]
	v_pk_fma_f32 v[138:139], v[18:19], v[138:139], v[138:139]
	v_div_fixup_f32 v136, v136, v132, 1.0
	v_div_fixup_f32 v137, v137, v133, 1.0
	v_div_fixup_f32 v138, v138, v134, 1.0
	v_div_fixup_f32 v139, v139, v135, 1.0
	v_cvt_pk_bf16_f32 v16, v136, v137
	v_cvt_pk_bf16_f32 v17, v138, v139
	ds_write_b64 v140, v[16:17] offset:192
	v_pk_mul_f32 v[132:133], v[20:21], s[12:13] op_sel_hi:[1,0]
	v_pk_mul_f32 v[134:135], v[22:23], s[12:13] op_sel_hi:[1,0]
	v_exp_f32_e32 v132, v132
	v_exp_f32_e32 v133, v133
	v_exp_f32_e32 v134, v134
	v_exp_f32_e32 v135, v135
	v_pk_add_f32 v[132:133], v[132:133], 1.0 op_sel_hi:[1,0]
	v_pk_add_f32 v[134:135], v[134:135], 1.0 op_sel_hi:[1,0]
	v_rcp_f32_e32 v136, v132
	v_rcp_f32_e32 v137, v133
	v_rcp_f32_e32 v138, v134
	v_rcp_f32_e32 v139, v135
	v_pk_fma_f32 v[20:21], v[132:133], v[136:137], 1.0 op_sel_hi:[1,1,0] neg_lo:[1,0,0] neg_hi:[1,0,0]
	v_pk_fma_f32 v[22:23], v[134:135], v[138:139], 1.0 op_sel_hi:[1,1,0] neg_lo:[1,0,0] neg_hi:[1,0,0]
	v_pk_fma_f32 v[136:137], v[20:21], v[136:137], v[136:137]
	v_pk_fma_f32 v[138:139], v[22:23], v[138:139], v[138:139]
	v_div_fixup_f32 v136, v136, v132, 1.0
	v_div_fixup_f32 v137, v137, v133, 1.0
	v_div_fixup_f32 v138, v138, v134, 1.0
	v_div_fixup_f32 v139, v139, v135, 1.0
	v_cvt_pk_bf16_f32 v20, v136, v137
	v_cvt_pk_bf16_f32 v21, v138, v139
	ds_write_b64 v140, v[20:21] offset:208
	v_pk_mul_f32 v[132:133], v[24:25], s[12:13] op_sel_hi:[1,0]
	v_pk_mul_f32 v[134:135], v[26:27], s[12:13] op_sel_hi:[1,0]
	v_exp_f32_e32 v132, v132
	v_exp_f32_e32 v133, v133
	v_exp_f32_e32 v134, v134
	v_exp_f32_e32 v135, v135
	v_pk_add_f32 v[132:133], v[132:133], 1.0 op_sel_hi:[1,0]
	v_pk_add_f32 v[134:135], v[134:135], 1.0 op_sel_hi:[1,0]
	v_rcp_f32_e32 v136, v132
	v_rcp_f32_e32 v137, v133
	v_rcp_f32_e32 v138, v134
	v_rcp_f32_e32 v139, v135
	v_pk_fma_f32 v[24:25], v[132:133], v[136:137], 1.0 op_sel_hi:[1,1,0] neg_lo:[1,0,0] neg_hi:[1,0,0]
	v_pk_fma_f32 v[26:27], v[134:135], v[138:139], 1.0 op_sel_hi:[1,1,0] neg_lo:[1,0,0] neg_hi:[1,0,0]
	v_pk_fma_f32 v[136:137], v[24:25], v[136:137], v[136:137]
	v_pk_fma_f32 v[138:139], v[26:27], v[138:139], v[138:139]
	v_div_fixup_f32 v136, v136, v132, 1.0
	v_div_fixup_f32 v137, v137, v133, 1.0
	v_div_fixup_f32 v138, v138, v134, 1.0
	v_div_fixup_f32 v139, v139, v135, 1.0
	v_cvt_pk_bf16_f32 v24, v136, v137
	v_cvt_pk_bf16_f32 v25, v138, v139
	ds_write_b64 v140, v[24:25] offset:224
	v_pk_mul_f32 v[132:133], v[28:29], s[12:13] op_sel_hi:[1,0]
	v_pk_mul_f32 v[134:135], v[30:31], s[12:13] op_sel_hi:[1,0]
	v_exp_f32_e32 v132, v132
	v_exp_f32_e32 v133, v133
	v_exp_f32_e32 v134, v134
	v_exp_f32_e32 v135, v135
	v_pk_add_f32 v[132:133], v[132:133], 1.0 op_sel_hi:[1,0]
	v_pk_add_f32 v[134:135], v[134:135], 1.0 op_sel_hi:[1,0]
	v_rcp_f32_e32 v136, v132
	v_rcp_f32_e32 v137, v133
	v_rcp_f32_e32 v138, v134
	v_rcp_f32_e32 v139, v135
	v_pk_fma_f32 v[28:29], v[132:133], v[136:137], 1.0 op_sel_hi:[1,1,0] neg_lo:[1,0,0] neg_hi:[1,0,0]
	v_pk_fma_f32 v[30:31], v[134:135], v[138:139], 1.0 op_sel_hi:[1,1,0] neg_lo:[1,0,0] neg_hi:[1,0,0]
	v_pk_fma_f32 v[136:137], v[28:29], v[136:137], v[136:137]
	v_pk_fma_f32 v[138:139], v[30:31], v[138:139], v[138:139]
	v_div_fixup_f32 v136, v136, v132, 1.0
	v_div_fixup_f32 v137, v137, v133, 1.0
	v_div_fixup_f32 v138, v138, v134, 1.0
	v_div_fixup_f32 v139, v139, v135, 1.0
	v_cvt_pk_bf16_f32 v28, v136, v137
	v_cvt_pk_bf16_f32 v29, v138, v139
	ds_write_b64 v140, v[28:29] offset:240
	ds_read_b128 v[144:147], v141 offset:0
	ds_read_b128 v[148:151], v141 offset:1088
	ds_read_b128 v[152:155], v141 offset:2176
	ds_read_b128 v[156:159], v141 offset:3264
	ds_read_b128 v[160:163], v141 offset:4352
	ds_read_b128 v[168:171], v141 offset:5440
	ds_read_b128 v[172:175], v141 offset:6528
	ds_read_b128 v[176:179], v141 offset:7616
	s_waitcnt lgkmcnt(7)
; DI float sigmoidf_(float x) { return 1.f / (1.f + __expf(-x)); }
; template <int WM>
; DI void inproj_tile(const Params& p, char* smem, const int m0, const int n0) {
;     ...
;   } else if (fw < 4352) {
; #pragma unroll
;     for (int i = 0; i < WM; ++i)
; #pragma unroll
;       for (int j = 0; j < 2; ++j)
; #pragma unroll
;         for (int q4 = 0; q4 < 4; ++q4) {
;           const int f = fw - 2304 + i * 32 + q4 * 8 + hh * 4;
;           const size_t t = tb + j * 32;
;           uint2 o;
;           o.x = pack2(sigmoidf_(acc[i][j][q4 * 4 + 0]), sigmoidf_(acc[i][j][q4 * 4 + 1]));
;           o.y = pack2(sigmoidf_(acc[i][j][q4 * 4 + 2]), sigmoidf_(acc[i][j][q4 * 4 + 3]));
;           *(uint2*)(MG + t * 2048 + f) = o;
;         }
	global_store_dwordx4 v142, v[144:147], s[8:9]
	v_add_u32_e32 v142, 0x4000, v142
	s_waitcnt lgkmcnt(6)
	global_store_dwordx4 v142, v[148:151], s[8:9]
	v_add_u32_e32 v142, 0x4000, v142
	s_waitcnt lgkmcnt(5)
	global_store_dwordx4 v142, v[152:155], s[8:9]
	v_add_u32_e32 v142, 0x4000, v142
	s_waitcnt lgkmcnt(4)
	global_store_dwordx4 v142, v[156:159], s[8:9]
	v_add_u32_e32 v142, 0x4000, v142
	s_waitcnt lgkmcnt(3)
	global_store_dwordx4 v142, v[160:163], s[8:9]
	v_add_u32_e32 v142, 0x4000, v142
	s_waitcnt lgkmcnt(2)
	global_store_dwordx4 v142, v[168:171], s[8:9]
	v_add_u32_e32 v142, 0x4000, v142
	s_waitcnt lgkmcnt(1)
	global_store_dwordx4 v142, v[172:175], s[8:9]
	v_add_u32_e32 v142, 0x4000, v142
	s_waitcnt lgkmcnt(0)
	global_store_dwordx4 v142, v[176:179], s[8:9]
	v_add_u32_e32 v142, 0x4000, v142
	v_pk_mul_f32 v[132:133], v[96:97], s[12:13] op_sel_hi:[1,0]
	v_pk_mul_f32 v[134:135], v[98:99], s[12:13] op_sel_hi:[1,0]
	v_exp_f32_e32 v132, v132
	v_exp_f32_e32 v133, v133
	v_exp_f32_e32 v134, v134
	v_exp_f32_e32 v135, v135
	v_pk_add_f32 v[132:133], v[132:133], 1.0 op_sel_hi:[1,0]
	v_pk_add_f32 v[134:135], v[134:135], 1.0 op_sel_hi:[1,0]
	v_rcp_f32_e32 v136, v132
	v_rcp_f32_e32 v137, v133
	v_rcp_f32_e32 v138, v134
	v_rcp_f32_e32 v139, v135
	v_pk_fma_f32 v[96:97], v[132:133], v[136:137], 1.0 op_sel_hi:[1,1,0] neg_lo:[1,0,0] neg_hi:[1,0,0]
	v_pk_fma_f32 v[98:99], v[134:135], v[138:139], 1.0 op_sel_hi:[1,1,0] neg_lo:[1,0,0] neg_hi:[1,0,0]
	v_pk_fma_f32 v[136:137], v[96:97], v[136:137], v[136:137]
	v_pk_fma_f32 v[138:139], v[98:99], v[138:139], v[138:139]
	v_div_fixup_f32 v136, v136, v132, 1.0
	v_div_fixup_f32 v137, v137, v133, 1.0
	v_div_fixup_f32 v138, v138, v134, 1.0
	v_div_fixup_f32 v139, v139, v135, 1.0
	v_cvt_pk_bf16_f32 v96, v136, v137
	v_cvt_pk_bf16_f32 v97, v138, v139
	ds_write_b64 v140, v[96:97] offset:8704
	v_pk_mul_f32 v[132:133], v[100:101], s[12:13] op_sel_hi:[1,0]
	v_pk_mul_f32 v[134:135], v[102:103], s[12:13] op_sel_hi:[1,0]
	v_exp_f32_e32 v132, v132
	v_exp_f32_e32 v133, v133
	v_exp_f32_e32 v134, v134
	v_exp_f32_e32 v135, v135
	v_pk_add_f32 v[132:133], v[132:133], 1.0 op_sel_hi:[1,0]
	v_pk_add_f32 v[134:135], v[134:135], 1.0 op_sel_hi:[1,0]
	v_rcp_f32_e32 v136, v132
	v_rcp_f32_e32 v137, v133
	v_rcp_f32_e32 v138, v134
	v_rcp_f32_e32 v139, v135
	v_pk_fma_f32 v[100:101], v[132:133], v[136:137], 1.0 op_sel_hi:[1,1,0] neg_lo:[1,0,0] neg_hi:[1,0,0]
	v_pk_fma_f32 v[102:103], v[134:135], v[138:139], 1.0 op_sel_hi:[1,1,0] neg_lo:[1,0,0] neg_hi:[1,0,0]
	v_pk_fma_f32 v[136:137], v[100:101], v[136:137], v[136:137]
	v_pk_fma_f32 v[138:139], v[102:103], v[138:139], v[138:139]
	v_div_fixup_f32 v136, v136, v132, 1.0
	v_div_fixup_f32 v137, v137, v133, 1.0
	v_div_fixup_f32 v138, v138, v134, 1.0
	v_div_fixup_f32 v139, v139, v135, 1.0
	v_cvt_pk_bf16_f32 v100, v136, v137
	v_cvt_pk_bf16_f32 v101, v138, v139
	ds_write_b64 v140, v[100:101] offset:8720
	v_pk_mul_f32 v[132:133], v[104:105], s[12:13] op_sel_hi:[1,0]
	v_pk_mul_f32 v[134:135], v[106:107], s[12:13] op_sel_hi:[1,0]
	v_exp_f32_e32 v132, v132
	v_exp_f32_e32 v133, v133
	v_exp_f32_e32 v134, v134
	v_exp_f32_e32 v135, v135
	v_pk_add_f32 v[132:133], v[132:133], 1.0 op_sel_hi:[1,0]
	v_pk_add_f32 v[134:135], v[134:135], 1.0 op_sel_hi:[1,0]
	v_rcp_f32_e32 v136, v132
	v_rcp_f32_e32 v137, v133
	v_rcp_f32_e32 v138, v134
	v_rcp_f32_e32 v139, v135
	v_pk_fma_f32 v[104:105], v[132:133], v[136:137], 1.0 op_sel_hi:[1,1,0] neg_lo:[1,0,0] neg_hi:[1,0,0]
	v_pk_fma_f32 v[106:107], v[134:135], v[138:139], 1.0 op_sel_hi:[1,1,0] neg_lo:[1,0,0] neg_hi:[1,0,0]
	v_pk_fma_f32 v[136:137], v[104:105], v[136:137], v[136:137]
	v_pk_fma_f32 v[138:139], v[106:107], v[138:139], v[138:139]
	v_div_fixup_f32 v136, v136, v132, 1.0
	v_div_fixup_f32 v137, v137, v133, 1.0
	v_div_fixup_f32 v138, v138, v134, 1.0
	v_div_fixup_f32 v139, v139, v135, 1.0
	v_cvt_pk_bf16_f32 v104, v136, v137
	v_cvt_pk_bf16_f32 v105, v138, v139
	ds_write_b64 v140, v[104:105] offset:8736
	v_pk_mul_f32 v[132:133], v[108:109], s[12:13] op_sel_hi:[1,0]
	v_pk_mul_f32 v[134:135], v[110:111], s[12:13] op_sel_hi:[1,0]
	v_exp_f32_e32 v132, v132
	v_exp_f32_e32 v133, v133
	v_exp_f32_e32 v134, v134
	v_exp_f32_e32 v135, v135
	v_pk_add_f32 v[132:133], v[132:133], 1.0 op_sel_hi:[1,0]
	v_pk_add_f32 v[134:135], v[134:135], 1.0 op_sel_hi:[1,0]
	v_rcp_f32_e32 v136, v132
	v_rcp_f32_e32 v137, v133
	v_rcp_f32_e32 v138, v134
	v_rcp_f32_e32 v139, v135
	v_pk_fma_f32 v[108:109], v[132:133], v[136:137], 1.0 op_sel_hi:[1,1,0] neg_lo:[1,0,0] neg_hi:[1,0,0]
	v_pk_fma_f32 v[110:111], v[134:135], v[138:139], 1.0 op_sel_hi:[1,1,0] neg_lo:[1,0,0] neg_hi:[1,0,0]
	v_pk_fma_f32 v[136:137], v[108:109], v[136:137], v[136:137]
	v_pk_fma_f32 v[138:139], v[110:111], v[138:139], v[138:139]
	v_div_fixup_f32 v136, v136, v132, 1.0
	v_div_fixup_f32 v137, v137, v133, 1.0
	v_div_fixup_f32 v138, v138, v134, 1.0
	v_div_fixup_f32 v139, v139, v135, 1.0
	v_cvt_pk_bf16_f32 v108, v136, v137
	v_cvt_pk_bf16_f32 v109, v138, v139
	ds_write_b64 v140, v[108:109] offset:8752
	v_pk_mul_f32 v[132:133], v[64:65], s[12:13] op_sel_hi:[1,0]
	v_pk_mul_f32 v[134:135], v[66:67], s[12:13] op_sel_hi:[1,0]
	v_exp_f32_e32 v132, v132
	v_exp_f32_e32 v133, v133
	v_exp_f32_e32 v134, v134
	v_exp_f32_e32 v135, v135
	v_pk_add_f32 v[132:133], v[132:133], 1.0 op_sel_hi:[1,0]
	v_pk_add_f32 v[134:135], v[134:135], 1.0 op_sel_hi:[1,0]
	v_rcp_f32_e32 v136, v132
	v_rcp_f32_e32 v137, v133
	v_rcp_f32_e32 v138, v134
	v_rcp_f32_e32 v139, v135
	v_pk_fma_f32 v[64:65], v[132:133], v[136:137], 1.0 op_sel_hi:[1,1,0] neg_lo:[1,0,0] neg_hi:[1,0,0]
	v_pk_fma_f32 v[66:67], v[134:135], v[138:139], 1.0 op_sel_hi:[1,1,0] neg_lo:[1,0,0] neg_hi:[1,0,0]
; DI float sigmoidf_(float x) { return 1.f / (1.f + __expf(-x)); }
; template <int WM>
; DI void inproj_tile(const Params& p, char* smem, const int m0, const int n0) {
;     ...
;   } else if (fw < 4352) {
; #pragma unroll
;     for (int i = 0; i < WM; ++i)
; #pragma unroll
;       for (int j = 0; j < 2; ++j)
; #pragma unroll
;         for (int q4 = 0; q4 < 4; ++q4) {
;           const int f = fw - 2304 + i * 32 + q4 * 8 + hh * 4;
;           const size_t t = tb + j * 32;
;           uint2 o;
;           o.x = pack2(sigmoidf_(acc[i][j][q4 * 4 + 0]), sigmoidf_(acc[i][j][q4 * 4 + 1]));
;           o.y = pack2(sigmoidf_(acc[i][j][q4 * 4 + 2]), sigmoidf_(acc[i][j][q4 * 4 + 3]));
;           *(uint2*)(MG + t * 2048 + f) = o;
;         }
	v_pk_fma_f32 v[136:137], v[64:65], v[136:137], v[136:137]
	v_pk_fma_f32 v[138:139], v[66:67], v[138:139], v[138:139]
	v_div_fixup_f32 v136, v136, v132, 1.0
	v_div_fixup_f32 v137, v137, v133, 1.0
	v_div_fixup_f32 v138, v138, v134, 1.0
	v_div_fixup_f32 v139, v139, v135, 1.0
	v_cvt_pk_bf16_f32 v64, v136, v137
	v_cvt_pk_bf16_f32 v65, v138, v139
	ds_write_b64 v140, v[64:65] offset:8768
	v_pk_mul_f32 v[132:133], v[68:69], s[12:13] op_sel_hi:[1,0]
	v_pk_mul_f32 v[134:135], v[70:71], s[12:13] op_sel_hi:[1,0]
	v_exp_f32_e32 v132, v132
	v_exp_f32_e32 v133, v133
	v_exp_f32_e32 v134, v134
	v_exp_f32_e32 v135, v135
	v_pk_add_f32 v[132:133], v[132:133], 1.0 op_sel_hi:[1,0]
	v_pk_add_f32 v[134:135], v[134:135], 1.0 op_sel_hi:[1,0]
	v_rcp_f32_e32 v136, v132
	v_rcp_f32_e32 v137, v133
	v_rcp_f32_e32 v138, v134
	v_rcp_f32_e32 v139, v135
	v_pk_fma_f32 v[68:69], v[132:133], v[136:137], 1.0 op_sel_hi:[1,1,0] neg_lo:[1,0,0] neg_hi:[1,0,0]
	v_pk_fma_f32 v[70:71], v[134:135], v[138:139], 1.0 op_sel_hi:[1,1,0] neg_lo:[1,0,0] neg_hi:[1,0,0]
	v_pk_fma_f32 v[136:137], v[68:69], v[136:137], v[136:137]
	v_pk_fma_f32 v[138:139], v[70:71], v[138:139], v[138:139]
	v_div_fixup_f32 v136, v136, v132, 1.0
	v_div_fixup_f32 v137, v137, v133, 1.0
	v_div_fixup_f32 v138, v138, v134, 1.0
	v_div_fixup_f32 v139, v139, v135, 1.0
	v_cvt_pk_bf16_f32 v68, v136, v137
	v_cvt_pk_bf16_f32 v69, v138, v139
	ds_write_b64 v140, v[68:69] offset:8784
	v_pk_mul_f32 v[132:133], v[72:73], s[12:13] op_sel_hi:[1,0]
	v_pk_mul_f32 v[134:135], v[74:75], s[12:13] op_sel_hi:[1,0]
	v_exp_f32_e32 v132, v132
	v_exp_f32_e32 v133, v133
	v_exp_f32_e32 v134, v134
	v_exp_f32_e32 v135, v135
	v_pk_add_f32 v[132:133], v[132:133], 1.0 op_sel_hi:[1,0]
	v_pk_add_f32 v[134:135], v[134:135], 1.0 op_sel_hi:[1,0]
	v_rcp_f32_e32 v136, v132
	v_rcp_f32_e32 v137, v133
	v_rcp_f32_e32 v138, v134
	v_rcp_f32_e32 v139, v135
	v_pk_fma_f32 v[72:73], v[132:133], v[136:137], 1.0 op_sel_hi:[1,1,0] neg_lo:[1,0,0] neg_hi:[1,0,0]
	v_pk_fma_f32 v[74:75], v[134:135], v[138:139], 1.0 op_sel_hi:[1,1,0] neg_lo:[1,0,0] neg_hi:[1,0,0]
	v_pk_fma_f32 v[136:137], v[72:73], v[136:137], v[136:137]
	v_pk_fma_f32 v[138:139], v[74:75], v[138:139], v[138:139]
	v_div_fixup_f32 v136, v136, v132, 1.0
	v_div_fixup_f32 v137, v137, v133, 1.0
	v_div_fixup_f32 v138, v138, v134, 1.0
	v_div_fixup_f32 v139, v139, v135, 1.0
	v_cvt_pk_bf16_f32 v72, v136, v137
	v_cvt_pk_bf16_f32 v73, v138, v139
	ds_write_b64 v140, v[72:73] offset:8800
	v_pk_mul_f32 v[132:133], v[76:77], s[12:13] op_sel_hi:[1,0]
	v_pk_mul_f32 v[134:135], v[78:79], s[12:13] op_sel_hi:[1,0]
	v_exp_f32_e32 v132, v132
	v_exp_f32_e32 v133, v133
	v_exp_f32_e32 v134, v134
	v_exp_f32_e32 v135, v135
	v_pk_add_f32 v[132:133], v[132:133], 1.0 op_sel_hi:[1,0]
	v_pk_add_f32 v[134:135], v[134:135], 1.0 op_sel_hi:[1,0]
	v_rcp_f32_e32 v136, v132
	v_rcp_f32_e32 v137, v133
	v_rcp_f32_e32 v138, v134
	v_rcp_f32_e32 v139, v135
	v_pk_fma_f32 v[76:77], v[132:133], v[136:137], 1.0 op_sel_hi:[1,1,0] neg_lo:[1,0,0] neg_hi:[1,0,0]
	v_pk_fma_f32 v[78:79], v[134:135], v[138:139], 1.0 op_sel_hi:[1,1,0] neg_lo:[1,0,0] neg_hi:[1,0,0]
	v_pk_fma_f32 v[136:137], v[76:77], v[136:137], v[136:137]
	v_pk_fma_f32 v[138:139], v[78:79], v[138:139], v[138:139]
	v_div_fixup_f32 v136, v136, v132, 1.0
	v_div_fixup_f32 v137, v137, v133, 1.0
	v_div_fixup_f32 v138, v138, v134, 1.0
	v_div_fixup_f32 v139, v139, v135, 1.0
	v_cvt_pk_bf16_f32 v76, v136, v137
	v_cvt_pk_bf16_f32 v77, v138, v139
	ds_write_b64 v140, v[76:77] offset:8816
	v_pk_mul_f32 v[132:133], v[32:33], s[12:13] op_sel_hi:[1,0]
	v_pk_mul_f32 v[134:135], v[34:35], s[12:13] op_sel_hi:[1,0]
	v_exp_f32_e32 v132, v132
	v_exp_f32_e32 v133, v133
	v_exp_f32_e32 v134, v134
	v_exp_f32_e32 v135, v135
	v_pk_add_f32 v[132:133], v[132:133], 1.0 op_sel_hi:[1,0]
	v_pk_add_f32 v[134:135], v[134:135], 1.0 op_sel_hi:[1,0]
	v_rcp_f32_e32 v136, v132
	v_rcp_f32_e32 v137, v133
	v_rcp_f32_e32 v138, v134
	v_rcp_f32_e32 v139, v135
	v_pk_fma_f32 v[32:33], v[132:133], v[136:137], 1.0 op_sel_hi:[1,1,0] neg_lo:[1,0,0] neg_hi:[1,0,0]
	v_pk_fma_f32 v[34:35], v[134:135], v[138:139], 1.0 op_sel_hi:[1,1,0] neg_lo:[1,0,0] neg_hi:[1,0,0]
	v_pk_fma_f32 v[136:137], v[32:33], v[136:137], v[136:137]
	v_pk_fma_f32 v[138:139], v[34:35], v[138:139], v[138:139]
	v_div_fixup_f32 v136, v136, v132, 1.0
	v_div_fixup_f32 v137, v137, v133, 1.0
	v_div_fixup_f32 v138, v138, v134, 1.0
	v_div_fixup_f32 v139, v139, v135, 1.0
	v_cvt_pk_bf16_f32 v32, v136, v137
	v_cvt_pk_bf16_f32 v33, v138, v139
	ds_write_b64 v140, v[32:33] offset:8832
	v_pk_mul_f32 v[132:133], v[36:37], s[12:13] op_sel_hi:[1,0]
	v_pk_mul_f32 v[134:135], v[38:39], s[12:13] op_sel_hi:[1,0]
	v_exp_f32_e32 v132, v132
	v_exp_f32_e32 v133, v133
	v_exp_f32_e32 v134, v134
	v_exp_f32_e32 v135, v135
	v_pk_add_f32 v[132:133], v[132:133], 1.0 op_sel_hi:[1,0]
	v_pk_add_f32 v[134:135], v[134:135], 1.0 op_sel_hi:[1,0]
	v_rcp_f32_e32 v136, v132
	v_rcp_f32_e32 v137, v133
	v_rcp_f32_e32 v138, v134
	v_rcp_f32_e32 v139, v135
	v_pk_fma_f32 v[36:37], v[132:133], v[136:137], 1.0 op_sel_hi:[1,1,0] neg_lo:[1,0,0] neg_hi:[1,0,0]
	v_pk_fma_f32 v[38:39], v[134:135], v[138:139], 1.0 op_sel_hi:[1,1,0] neg_lo:[1,0,0] neg_hi:[1,0,0]
	v_pk_fma_f32 v[136:137], v[36:37], v[136:137], v[136:137]
	v_pk_fma_f32 v[138:139], v[38:39], v[138:139], v[138:139]
	v_div_fixup_f32 v136, v136, v132, 1.0
	v_div_fixup_f32 v137, v137, v133, 1.0
	v_div_fixup_f32 v138, v138, v134, 1.0
	v_div_fixup_f32 v139, v139, v135, 1.0
	v_cvt_pk_bf16_f32 v36, v136, v137
	v_cvt_pk_bf16_f32 v37, v138, v139
	ds_write_b64 v140, v[36:37] offset:8848
	v_pk_mul_f32 v[132:133], v[40:41], s[12:13] op_sel_hi:[1,0]
	v_pk_mul_f32 v[134:135], v[42:43], s[12:13] op_sel_hi:[1,0]
; DI float sigmoidf_(float x) { return 1.f / (1.f + __expf(-x)); }
; template <int WM>
; DI void inproj_tile(const Params& p, char* smem, const int m0, const int n0) {
;     ...
;   } else if (fw < 4352) {
; #pragma unroll
;     for (int i = 0; i < WM; ++i)
; #pragma unroll
;       for (int j = 0; j < 2; ++j)
; #pragma unroll
;         for (int q4 = 0; q4 < 4; ++q4) {
;           const int f = fw - 2304 + i * 32 + q4 * 8 + hh * 4;
;           const size_t t = tb + j * 32;
;           uint2 o;
;           o.x = pack2(sigmoidf_(acc[i][j][q4 * 4 + 0]), sigmoidf_(acc[i][j][q4 * 4 + 1]));
;           o.y = pack2(sigmoidf_(acc[i][j][q4 * 4 + 2]), sigmoidf_(acc[i][j][q4 * 4 + 3]));
;           *(uint2*)(MG + t * 2048 + f) = o;
;         }
	v_exp_f32_e32 v132, v132
	v_exp_f32_e32 v133, v133
	v_exp_f32_e32 v134, v134
	v_exp_f32_e32 v135, v135
	v_pk_add_f32 v[132:133], v[132:133], 1.0 op_sel_hi:[1,0]
	v_pk_add_f32 v[134:135], v[134:135], 1.0 op_sel_hi:[1,0]
	v_rcp_f32_e32 v136, v132
	v_rcp_f32_e32 v137, v133
	v_rcp_f32_e32 v138, v134
	v_rcp_f32_e32 v139, v135
	v_pk_fma_f32 v[40:41], v[132:133], v[136:137], 1.0 op_sel_hi:[1,1,0] neg_lo:[1,0,0] neg_hi:[1,0,0]
	v_pk_fma_f32 v[42:43], v[134:135], v[138:139], 1.0 op_sel_hi:[1,1,0] neg_lo:[1,0,0] neg_hi:[1,0,0]
	v_pk_fma_f32 v[136:137], v[40:41], v[136:137], v[136:137]
	v_pk_fma_f32 v[138:139], v[42:43], v[138:139], v[138:139]
	v_div_fixup_f32 v136, v136, v132, 1.0
	v_div_fixup_f32 v137, v137, v133, 1.0
	v_div_fixup_f32 v138, v138, v134, 1.0
	v_div_fixup_f32 v139, v139, v135, 1.0
	v_cvt_pk_bf16_f32 v40, v136, v137
	v_cvt_pk_bf16_f32 v41, v138, v139
	ds_write_b64 v140, v[40:41] offset:8864
	v_pk_mul_f32 v[132:133], v[44:45], s[12:13] op_sel_hi:[1,0]
	v_pk_mul_f32 v[134:135], v[46:47], s[12:13] op_sel_hi:[1,0]
	v_exp_f32_e32 v132, v132
	v_exp_f32_e32 v133, v133
	v_exp_f32_e32 v134, v134
	v_exp_f32_e32 v135, v135
	v_pk_add_f32 v[132:133], v[132:133], 1.0 op_sel_hi:[1,0]
	v_pk_add_f32 v[134:135], v[134:135], 1.0 op_sel_hi:[1,0]
	v_rcp_f32_e32 v136, v132
	v_rcp_f32_e32 v137, v133
	v_rcp_f32_e32 v138, v134
	v_rcp_f32_e32 v139, v135
	v_pk_fma_f32 v[44:45], v[132:133], v[136:137], 1.0 op_sel_hi:[1,1,0] neg_lo:[1,0,0] neg_hi:[1,0,0]
	v_pk_fma_f32 v[46:47], v[134:135], v[138:139], 1.0 op_sel_hi:[1,1,0] neg_lo:[1,0,0] neg_hi:[1,0,0]
	v_pk_fma_f32 v[136:137], v[44:45], v[136:137], v[136:137]
	v_pk_fma_f32 v[138:139], v[46:47], v[138:139], v[138:139]
	v_div_fixup_f32 v136, v136, v132, 1.0
	v_div_fixup_f32 v137, v137, v133, 1.0
	v_div_fixup_f32 v138, v138, v134, 1.0
	v_div_fixup_f32 v139, v139, v135, 1.0
	v_cvt_pk_bf16_f32 v44, v136, v137
	v_cvt_pk_bf16_f32 v45, v138, v139
	ds_write_b64 v140, v[44:45] offset:8880
	v_pk_mul_f32 v[132:133], v[0:1], s[12:13] op_sel_hi:[1,0]
	v_pk_mul_f32 v[134:135], v[2:3], s[12:13] op_sel_hi:[1,0]
	v_exp_f32_e32 v132, v132
	v_exp_f32_e32 v133, v133
	v_exp_f32_e32 v134, v134
	v_exp_f32_e32 v135, v135
	v_pk_add_f32 v[132:133], v[132:133], 1.0 op_sel_hi:[1,0]
	v_pk_add_f32 v[134:135], v[134:135], 1.0 op_sel_hi:[1,0]
	v_rcp_f32_e32 v136, v132
	v_rcp_f32_e32 v137, v133
	v_rcp_f32_e32 v138, v134
	v_rcp_f32_e32 v139, v135
	v_pk_fma_f32 v[0:1], v[132:133], v[136:137], 1.0 op_sel_hi:[1,1,0] neg_lo:[1,0,0] neg_hi:[1,0,0]
	v_pk_fma_f32 v[2:3], v[134:135], v[138:139], 1.0 op_sel_hi:[1,1,0] neg_lo:[1,0,0] neg_hi:[1,0,0]
	v_pk_fma_f32 v[136:137], v[0:1], v[136:137], v[136:137]
	v_pk_fma_f32 v[138:139], v[2:3], v[138:139], v[138:139]
	v_div_fixup_f32 v136, v136, v132, 1.0
	v_div_fixup_f32 v137, v137, v133, 1.0
	v_div_fixup_f32 v138, v138, v134, 1.0
	v_div_fixup_f32 v139, v139, v135, 1.0
	v_cvt_pk_bf16_f32 v0, v136, v137
	v_cvt_pk_bf16_f32 v1, v138, v139
	ds_write_b64 v140, v[0:1] offset:8896
	v_pk_mul_f32 v[132:133], v[4:5], s[12:13] op_sel_hi:[1,0]
	v_pk_mul_f32 v[134:135], v[6:7], s[12:13] op_sel_hi:[1,0]
	v_exp_f32_e32 v132, v132
	v_exp_f32_e32 v133, v133
	v_exp_f32_e32 v134, v134
	v_exp_f32_e32 v135, v135
	v_pk_add_f32 v[132:133], v[132:133], 1.0 op_sel_hi:[1,0]
	v_pk_add_f32 v[134:135], v[134:135], 1.0 op_sel_hi:[1,0]
	v_rcp_f32_e32 v136, v132
	v_rcp_f32_e32 v137, v133
	v_rcp_f32_e32 v138, v134
	v_rcp_f32_e32 v139, v135
	v_pk_fma_f32 v[4:5], v[132:133], v[136:137], 1.0 op_sel_hi:[1,1,0] neg_lo:[1,0,0] neg_hi:[1,0,0]
	v_pk_fma_f32 v[6:7], v[134:135], v[138:139], 1.0 op_sel_hi:[1,1,0] neg_lo:[1,0,0] neg_hi:[1,0,0]
	v_pk_fma_f32 v[136:137], v[4:5], v[136:137], v[136:137]
	v_pk_fma_f32 v[138:139], v[6:7], v[138:139], v[138:139]
	v_div_fixup_f32 v136, v136, v132, 1.0
	v_div_fixup_f32 v137, v137, v133, 1.0
	v_div_fixup_f32 v138, v138, v134, 1.0
	v_div_fixup_f32 v139, v139, v135, 1.0
	v_cvt_pk_bf16_f32 v4, v136, v137
	v_cvt_pk_bf16_f32 v5, v138, v139
	ds_write_b64 v140, v[4:5] offset:8912
	v_pk_mul_f32 v[132:133], v[8:9], s[12:13] op_sel_hi:[1,0]
	v_pk_mul_f32 v[134:135], v[10:11], s[12:13] op_sel_hi:[1,0]
	v_exp_f32_e32 v132, v132
	v_exp_f32_e32 v133, v133
	v_exp_f32_e32 v134, v134
	v_exp_f32_e32 v135, v135
	v_pk_add_f32 v[132:133], v[132:133], 1.0 op_sel_hi:[1,0]
	v_pk_add_f32 v[134:135], v[134:135], 1.0 op_sel_hi:[1,0]
	v_rcp_f32_e32 v136, v132
	v_rcp_f32_e32 v137, v133
	v_rcp_f32_e32 v138, v134
	v_rcp_f32_e32 v139, v135
	v_pk_fma_f32 v[8:9], v[132:133], v[136:137], 1.0 op_sel_hi:[1,1,0] neg_lo:[1,0,0] neg_hi:[1,0,0]
	v_pk_fma_f32 v[10:11], v[134:135], v[138:139], 1.0 op_sel_hi:[1,1,0] neg_lo:[1,0,0] neg_hi:[1,0,0]
	v_pk_fma_f32 v[136:137], v[8:9], v[136:137], v[136:137]
	v_pk_fma_f32 v[138:139], v[10:11], v[138:139], v[138:139]
	v_div_fixup_f32 v136, v136, v132, 1.0
	v_div_fixup_f32 v137, v137, v133, 1.0
	v_div_fixup_f32 v138, v138, v134, 1.0
	v_div_fixup_f32 v139, v139, v135, 1.0
	v_cvt_pk_bf16_f32 v8, v136, v137
	v_cvt_pk_bf16_f32 v9, v138, v139
	ds_write_b64 v140, v[8:9] offset:8928
	v_pk_mul_f32 v[132:133], v[12:13], s[12:13] op_sel_hi:[1,0]
	v_pk_mul_f32 v[134:135], v[14:15], s[12:13] op_sel_hi:[1,0]
	v_exp_f32_e32 v132, v132
	v_exp_f32_e32 v133, v133
	v_exp_f32_e32 v134, v134
	v_exp_f32_e32 v135, v135
	v_pk_add_f32 v[132:133], v[132:133], 1.0 op_sel_hi:[1,0]
	v_pk_add_f32 v[134:135], v[134:135], 1.0 op_sel_hi:[1,0]
	v_rcp_f32_e32 v136, v132
	v_rcp_f32_e32 v137, v133
	v_rcp_f32_e32 v138, v134
	v_rcp_f32_e32 v139, v135
	v_pk_fma_f32 v[12:13], v[132:133], v[136:137], 1.0 op_sel_hi:[1,1,0] neg_lo:[1,0,0] neg_hi:[1,0,0]
	v_pk_fma_f32 v[14:15], v[134:135], v[138:139], 1.0 op_sel_hi:[1,1,0] neg_lo:[1,0,0] neg_hi:[1,0,0]
	v_pk_fma_f32 v[136:137], v[12:13], v[136:137], v[136:137]
	v_pk_fma_f32 v[138:139], v[14:15], v[138:139], v[138:139]
	v_div_fixup_f32 v136, v136, v132, 1.0
	v_div_fixup_f32 v137, v137, v133, 1.0
	v_div_fixup_f32 v138, v138, v134, 1.0
	v_div_fixup_f32 v139, v139, v135, 1.0
	v_cvt_pk_bf16_f32 v12, v136, v137
	v_cvt_pk_bf16_f32 v13, v138, v139
	ds_write_b64 v140, v[12:13] offset:8944
	ds_read_b128 v[144:147], v141 offset:8704
	ds_read_b128 v[148:151], v141 offset:9792
	ds_read_b128 v[152:155], v141 offset:10880
	ds_read_b128 v[156:159], v141 offset:11968
	ds_read_b128 v[160:163], v141 offset:13056
	ds_read_b128 v[168:171], v141 offset:14144
	ds_read_b128 v[172:175], v141 offset:15232
	ds_read_b128 v[176:179], v141 offset:16320
	s_waitcnt lgkmcnt(7)
; DI float sigmoidf_(float x) { return 1.f / (1.f + __expf(-x)); }
; template <int WM>
; DI void inproj_tile(const Params& p, char* smem, const int m0, const int n0) {
;     ...
;   } else if (fw < 4352) {
; #pragma unroll
;     for (int i = 0; i < WM; ++i)
; #pragma unroll
;       for (int j = 0; j < 2; ++j)
; #pragma unroll
;         for (int q4 = 0; q4 < 4; ++q4) {
;           const int f = fw - 2304 + i * 32 + q4 * 8 + hh * 4;
;           const size_t t = tb + j * 32;
;           uint2 o;
;           o.x = pack2(sigmoidf_(acc[i][j][q4 * 4 + 0]), sigmoidf_(acc[i][j][q4 * 4 + 1]));
;           o.y = pack2(sigmoidf_(acc[i][j][q4 * 4 + 2]), sigmoidf_(acc[i][j][q4 * 4 + 3]));
;           *(uint2*)(MG + t * 2048 + f) = o;
;         }
	global_store_dwordx4 v142, v[144:147], s[8:9]
	v_add_u32_e32 v142, 0x4000, v142
	s_waitcnt lgkmcnt(6)
	global_store_dwordx4 v142, v[148:151], s[8:9]
	v_add_u32_e32 v142, 0x4000, v142
	s_waitcnt lgkmcnt(5)
	global_store_dwordx4 v142, v[152:155], s[8:9]
	v_add_u32_e32 v142, 0x4000, v142
	s_waitcnt lgkmcnt(4)
	global_store_dwordx4 v142, v[156:159], s[8:9]
	v_add_u32_e32 v142, 0x4000, v142
	s_waitcnt lgkmcnt(3)
	global_store_dwordx4 v142, v[160:163], s[8:9]
	v_add_u32_e32 v142, 0x4000, v142
	s_waitcnt lgkmcnt(2)
	global_store_dwordx4 v142, v[168:171], s[8:9]
	v_add_u32_e32 v142, 0x4000, v142
	s_waitcnt lgkmcnt(1)
	global_store_dwordx4 v142, v[172:175], s[8:9]
	v_add_u32_e32 v142, 0x4000, v142
	s_waitcnt lgkmcnt(0)
	global_store_dwordx4 v142, v[176:179], s[8:9]
	v_add_u32_e32 v142, 0x4000, v142

; DI float sigmoidf_(float x) { return 1.f / (1.f + __expf(-x)); }
; template <int WM>
; DI void inproj_tile(const Params& p, char* smem, const int m0, const int n0) {
;     ...
;   } else if (fw < 2304) {
;     if (WM == 4) {
;       const int blk = (fw - 1280) >> 7;
; #pragma unroll
;       for (int i = 0; i < 2; ++i)
; #pragma unroll
;         for (int j = 0; j < 2; ++j)
; #pragma unroll
;           for (int q4 = 0; q4 < 4; ++q4) {
;             const int ch = blk * 64 + i * 32 + q4 * 8 + hh * 4;
;             const size_t t = tb + j * 32;
;             float u[4];
; #pragma unroll
;             for (int z = 0; z < 4; ++z) u[z] = acc[i][j][q4 * 4 + z] * sigmoidf_(acc[(i + 2) & (WM - 1)][j][q4 * 4 + z]);
;             uint2 o;
;             o.x = pack2(u[0], u[1]);
;             o.y = pack2(u[2], u[3]);
;             *(uint2*)(GLU + t * 512 + ch) = o;
;           }
;     }
.LBB0_177:
	s_andn2_saveexec_b64 s[20:21], s[20:21]
	s_cbranch_execz .LBB0_179
	s_waitcnt vmcnt(0)
	v_mbcnt_lo_u32_b32 v143, -1, 0
	v_mbcnt_hi_u32_b32 v143, -1, v143
	v_lshrrev_b32_e32 v132, 6, v211
	v_mul_u32_u24_e32 v132, 9216, v132
	v_and_b32_e32 v133, 31, v143
	v_lshrrev_b32_e32 v134, 5, v143
	v_mul_u32_u24_e32 v133, 144, v133
	v_lshl_add_u32 v133, v134, 3, v133
	v_add3_u32 v140, v133, v132, 64
	v_lshrrev_b32_e32 v135, 3, v143
	v_and_b32_e32 v136, 7, v143
	v_mul_u32_u24_e32 v137, 144, v135
	v_lshl_add_u32 v137, v136, 4, v137
	v_add3_u32 v141, v137, v132, 64
	v_and_b32_e32 v138, 0xffffffe0, v129
	v_add_u32_e32 v138, v138, v135
	v_lshlrev_b32_e32 v138, 10, v138
	v_add_u32_e32 v139, 4294966016, v131
	v_lshl_add_u32 v138, v139, 0, v138
	v_lshl_add_u32 v142, v136, 4, v138
	s_mov_b32 s12, 0xbfb8aa3b
	v_pk_mul_f32 v[132:133], v[48:49], s[12:13] op_sel_hi:[1,0]
	v_pk_mul_f32 v[134:135], v[50:51], s[12:13] op_sel_hi:[1,0]
	v_exp_f32_e32 v132, v132
	v_exp_f32_e32 v133, v133
	v_exp_f32_e32 v134, v134
	v_exp_f32_e32 v135, v135
	v_pk_add_f32 v[132:133], v[132:133], 1.0 op_sel_hi:[1,0]
	v_pk_add_f32 v[134:135], v[134:135], 1.0 op_sel_hi:[1,0]
	v_rcp_f32_e32 v136, v132
	v_rcp_f32_e32 v137, v133
	v_rcp_f32_e32 v138, v134
	v_rcp_f32_e32 v139, v135
	v_pk_fma_f32 v[48:49], v[132:133], v[136:137], 1.0 op_sel_hi:[1,1,0] neg_lo:[1,0,0] neg_hi:[1,0,0]
	v_pk_fma_f32 v[50:51], v[134:135], v[138:139], 1.0 op_sel_hi:[1,1,0] neg_lo:[1,0,0] neg_hi:[1,0,0]
	v_pk_fma_f32 v[136:137], v[48:49], v[136:137], v[136:137]
	v_pk_fma_f32 v[138:139], v[50:51], v[138:139], v[138:139]
	v_div_fixup_f32 v136, v136, v132, 1.0
	v_div_fixup_f32 v137, v137, v133, 1.0
	v_div_fixup_f32 v138, v138, v134, 1.0
	v_div_fixup_f32 v139, v139, v135, 1.0
	v_pk_mul_f32 v[136:137], v[112:113], v[136:137]
	v_pk_mul_f32 v[138:139], v[114:115], v[138:139]
	v_cvt_pk_bf16_f32 v112, v136, v137
	v_cvt_pk_bf16_f32 v113, v138, v139
	ds_write_b64 v140, v[112:113] offset:0
	v_pk_mul_f32 v[132:133], v[52:53], s[12:13] op_sel_hi:[1,0]
	v_pk_mul_f32 v[134:135], v[54:55], s[12:13] op_sel_hi:[1,0]
	v_exp_f32_e32 v132, v132
	v_exp_f32_e32 v133, v133
	v_exp_f32_e32 v134, v134
	v_exp_f32_e32 v135, v135
	v_pk_add_f32 v[132:133], v[132:133], 1.0 op_sel_hi:[1,0]
	v_pk_add_f32 v[134:135], v[134:135], 1.0 op_sel_hi:[1,0]
	v_rcp_f32_e32 v136, v132
	v_rcp_f32_e32 v137, v133
	v_rcp_f32_e32 v138, v134
	v_rcp_f32_e32 v139, v135
	v_pk_fma_f32 v[52:53], v[132:133], v[136:137], 1.0 op_sel_hi:[1,1,0] neg_lo:[1,0,0] neg_hi:[1,0,0]
	v_pk_fma_f32 v[54:55], v[134:135], v[138:139], 1.0 op_sel_hi:[1,1,0] neg_lo:[1,0,0] neg_hi:[1,0,0]
	v_pk_fma_f32 v[136:137], v[52:53], v[136:137], v[136:137]
	v_pk_fma_f32 v[138:139], v[54:55], v[138:139], v[138:139]
	v_div_fixup_f32 v136, v136, v132, 1.0
	v_div_fixup_f32 v137, v137, v133, 1.0
	v_div_fixup_f32 v138, v138, v134, 1.0
	v_div_fixup_f32 v139, v139, v135, 1.0
	v_pk_mul_f32 v[136:137], v[116:117], v[136:137]
	v_pk_mul_f32 v[138:139], v[118:119], v[138:139]
	v_cvt_pk_bf16_f32 v116, v136, v137
	v_cvt_pk_bf16_f32 v117, v138, v139
	ds_write_b64 v140, v[116:117] offset:16
	v_pk_mul_f32 v[132:133], v[56:57], s[12:13] op_sel_hi:[1,0]
	v_pk_mul_f32 v[134:135], v[58:59], s[12:13] op_sel_hi:[1,0]
	v_exp_f32_e32 v132, v132
	v_exp_f32_e32 v133, v133
	v_exp_f32_e32 v134, v134
	v_exp_f32_e32 v135, v135
	v_pk_add_f32 v[132:133], v[132:133], 1.0 op_sel_hi:[1,0]
	v_pk_add_f32 v[134:135], v[134:135], 1.0 op_sel_hi:[1,0]
	v_rcp_f32_e32 v136, v132
	v_rcp_f32_e32 v137, v133
	v_rcp_f32_e32 v138, v134
	v_rcp_f32_e32 v139, v135
	v_pk_fma_f32 v[56:57], v[132:133], v[136:137], 1.0 op_sel_hi:[1,1,0] neg_lo:[1,0,0] neg_hi:[1,0,0]
	v_pk_fma_f32 v[58:59], v[134:135], v[138:139], 1.0 op_sel_hi:[1,1,0] neg_lo:[1,0,0] neg_hi:[1,0,0]
	v_pk_fma_f32 v[136:137], v[56:57], v[136:137], v[136:137]
	v_pk_fma_f32 v[138:139], v[58:59], v[138:139], v[138:139]
	v_div_fixup_f32 v136, v136, v132, 1.0
	v_div_fixup_f32 v137, v137, v133, 1.0
	v_div_fixup_f32 v138, v138, v134, 1.0
	v_div_fixup_f32 v139, v139, v135, 1.0
	v_pk_mul_f32 v[136:137], v[120:121], v[136:137]
	v_pk_mul_f32 v[138:139], v[122:123], v[138:139]
	v_cvt_pk_bf16_f32 v120, v136, v137
	v_cvt_pk_bf16_f32 v121, v138, v139
	ds_write_b64 v140, v[120:121] offset:32
	v_pk_mul_f32 v[132:133], v[60:61], s[12:13] op_sel_hi:[1,0]
	v_pk_mul_f32 v[134:135], v[62:63], s[12:13] op_sel_hi:[1,0]
	v_exp_f32_e32 v132, v132
	v_exp_f32_e32 v133, v133
	v_exp_f32_e32 v134, v134
	v_exp_f32_e32 v135, v135
	v_pk_add_f32 v[132:133], v[132:133], 1.0 op_sel_hi:[1,0]
	v_pk_add_f32 v[134:135], v[134:135], 1.0 op_sel_hi:[1,0]
	v_rcp_f32_e32 v136, v132
	v_rcp_f32_e32 v137, v133
	v_rcp_f32_e32 v138, v134
	v_rcp_f32_e32 v139, v135
	v_pk_fma_f32 v[60:61], v[132:133], v[136:137], 1.0 op_sel_hi:[1,1,0] neg_lo:[1,0,0] neg_hi:[1,0,0]
	v_pk_fma_f32 v[62:63], v[134:135], v[138:139], 1.0 op_sel_hi:[1,1,0] neg_lo:[1,0,0] neg_hi:[1,0,0]
	v_pk_fma_f32 v[136:137], v[60:61], v[136:137], v[136:137]
	v_pk_fma_f32 v[138:139], v[62:63], v[138:139], v[138:139]
	v_div_fixup_f32 v136, v136, v132, 1.0
	v_div_fixup_f32 v137, v137, v133, 1.0
	v_div_fixup_f32 v138, v138, v134, 1.0
	v_div_fixup_f32 v139, v139, v135, 1.0
	v_pk_mul_f32 v[136:137], v[124:125], v[136:137]
	v_pk_mul_f32 v[138:139], v[126:127], v[138:139]
	v_cvt_pk_bf16_f32 v124, v136, v137
	v_cvt_pk_bf16_f32 v125, v138, v139
	ds_write_b64 v140, v[124:125] offset:48
	v_pk_mul_f32 v[132:133], v[16:17], s[12:13] op_sel_hi:[1,0]
	v_pk_mul_f32 v[134:135], v[18:19], s[12:13] op_sel_hi:[1,0]
	v_exp_f32_e32 v132, v132
	v_exp_f32_e32 v133, v133
	v_exp_f32_e32 v134, v134
	v_exp_f32_e32 v135, v135
	v_pk_add_f32 v[132:133], v[132:133], 1.0 op_sel_hi:[1,0]
; DI float sigmoidf_(float x) { return 1.f / (1.f + __expf(-x)); }
; template <int WM>
; DI void inproj_tile(const Params& p, char* smem, const int m0, const int n0) {
;     ...
;   } else if (fw < 2304) {
;     if (WM == 4) {
;       const int blk = (fw - 1280) >> 7;
; #pragma unroll
;       for (int i = 0; i < 2; ++i)
; #pragma unroll
;         for (int j = 0; j < 2; ++j)
; #pragma unroll
;           for (int q4 = 0; q4 < 4; ++q4) {
;             const int ch = blk * 64 + i * 32 + q4 * 8 + hh * 4;
;             const size_t t = tb + j * 32;
;             float u[4];
; #pragma unroll
;             for (int z = 0; z < 4; ++z) u[z] = acc[i][j][q4 * 4 + z] * sigmoidf_(acc[(i + 2) & (WM - 1)][j][q4 * 4 + z]);
;             uint2 o;
;             o.x = pack2(u[0], u[1]);
;             o.y = pack2(u[2], u[3]);
;             *(uint2*)(GLU + t * 512 + ch) = o;
;           }
;     }
	v_pk_add_f32 v[134:135], v[134:135], 1.0 op_sel_hi:[1,0]
	v_rcp_f32_e32 v136, v132
	v_rcp_f32_e32 v137, v133
	v_rcp_f32_e32 v138, v134
	v_rcp_f32_e32 v139, v135
	v_pk_fma_f32 v[16:17], v[132:133], v[136:137], 1.0 op_sel_hi:[1,1,0] neg_lo:[1,0,0] neg_hi:[1,0,0]
	v_pk_fma_f32 v[18:19], v[134:135], v[138:139], 1.0 op_sel_hi:[1,1,0] neg_lo:[1,0,0] neg_hi:[1,0,0]
	v_pk_fma_f32 v[136:137], v[16:17], v[136:137], v[136:137]
	v_pk_fma_f32 v[138:139], v[18:19], v[138:139], v[138:139]
	v_div_fixup_f32 v136, v136, v132, 1.0
	v_div_fixup_f32 v137, v137, v133, 1.0
	v_div_fixup_f32 v138, v138, v134, 1.0
	v_div_fixup_f32 v139, v139, v135, 1.0
	v_pk_mul_f32 v[136:137], v[80:81], v[136:137]
	v_pk_mul_f32 v[138:139], v[82:83], v[138:139]
	v_cvt_pk_bf16_f32 v80, v136, v137
	v_cvt_pk_bf16_f32 v81, v138, v139
	ds_write_b64 v140, v[80:81] offset:64
	v_pk_mul_f32 v[132:133], v[20:21], s[12:13] op_sel_hi:[1,0]
	v_pk_mul_f32 v[134:135], v[22:23], s[12:13] op_sel_hi:[1,0]
	v_exp_f32_e32 v132, v132
	v_exp_f32_e32 v133, v133
	v_exp_f32_e32 v134, v134
	v_exp_f32_e32 v135, v135
	v_pk_add_f32 v[132:133], v[132:133], 1.0 op_sel_hi:[1,0]
	v_pk_add_f32 v[134:135], v[134:135], 1.0 op_sel_hi:[1,0]
	v_rcp_f32_e32 v136, v132
	v_rcp_f32_e32 v137, v133
	v_rcp_f32_e32 v138, v134
	v_rcp_f32_e32 v139, v135
	v_pk_fma_f32 v[20:21], v[132:133], v[136:137], 1.0 op_sel_hi:[1,1,0] neg_lo:[1,0,0] neg_hi:[1,0,0]
	v_pk_fma_f32 v[22:23], v[134:135], v[138:139], 1.0 op_sel_hi:[1,1,0] neg_lo:[1,0,0] neg_hi:[1,0,0]
	v_pk_fma_f32 v[136:137], v[20:21], v[136:137], v[136:137]
	v_pk_fma_f32 v[138:139], v[22:23], v[138:139], v[138:139]
	v_div_fixup_f32 v136, v136, v132, 1.0
	v_div_fixup_f32 v137, v137, v133, 1.0
	v_div_fixup_f32 v138, v138, v134, 1.0
	v_div_fixup_f32 v139, v139, v135, 1.0
	v_pk_mul_f32 v[136:137], v[84:85], v[136:137]
	v_pk_mul_f32 v[138:139], v[86:87], v[138:139]
	v_cvt_pk_bf16_f32 v84, v136, v137
	v_cvt_pk_bf16_f32 v85, v138, v139
	ds_write_b64 v140, v[84:85] offset:80
	v_pk_mul_f32 v[132:133], v[24:25], s[12:13] op_sel_hi:[1,0]
	v_pk_mul_f32 v[134:135], v[26:27], s[12:13] op_sel_hi:[1,0]
	v_exp_f32_e32 v132, v132
	v_exp_f32_e32 v133, v133
	v_exp_f32_e32 v134, v134
	v_exp_f32_e32 v135, v135
	v_pk_add_f32 v[132:133], v[132:133], 1.0 op_sel_hi:[1,0]
	v_pk_add_f32 v[134:135], v[134:135], 1.0 op_sel_hi:[1,0]
	v_rcp_f32_e32 v136, v132
	v_rcp_f32_e32 v137, v133
	v_rcp_f32_e32 v138, v134
	v_rcp_f32_e32 v139, v135
	v_pk_fma_f32 v[24:25], v[132:133], v[136:137], 1.0 op_sel_hi:[1,1,0] neg_lo:[1,0,0] neg_hi:[1,0,0]
	v_pk_fma_f32 v[26:27], v[134:135], v[138:139], 1.0 op_sel_hi:[1,1,0] neg_lo:[1,0,0] neg_hi:[1,0,0]
	v_pk_fma_f32 v[136:137], v[24:25], v[136:137], v[136:137]
	v_pk_fma_f32 v[138:139], v[26:27], v[138:139], v[138:139]
	v_div_fixup_f32 v136, v136, v132, 1.0
	v_div_fixup_f32 v137, v137, v133, 1.0
	v_div_fixup_f32 v138, v138, v134, 1.0
	v_div_fixup_f32 v139, v139, v135, 1.0
	v_pk_mul_f32 v[136:137], v[88:89], v[136:137]
	v_pk_mul_f32 v[138:139], v[90:91], v[138:139]
	v_cvt_pk_bf16_f32 v88, v136, v137
	v_cvt_pk_bf16_f32 v89, v138, v139
	ds_write_b64 v140, v[88:89] offset:96
	v_pk_mul_f32 v[132:133], v[28:29], s[12:13] op_sel_hi:[1,0]
	v_pk_mul_f32 v[134:135], v[30:31], s[12:13] op_sel_hi:[1,0]
	v_exp_f32_e32 v132, v132
	v_exp_f32_e32 v133, v133
	v_exp_f32_e32 v134, v134
	v_exp_f32_e32 v135, v135
	v_pk_add_f32 v[132:133], v[132:133], 1.0 op_sel_hi:[1,0]
	v_pk_add_f32 v[134:135], v[134:135], 1.0 op_sel_hi:[1,0]
	v_rcp_f32_e32 v136, v132
	v_rcp_f32_e32 v137, v133
	v_rcp_f32_e32 v138, v134
	v_rcp_f32_e32 v139, v135
	v_pk_fma_f32 v[28:29], v[132:133], v[136:137], 1.0 op_sel_hi:[1,1,0] neg_lo:[1,0,0] neg_hi:[1,0,0]
	v_pk_fma_f32 v[30:31], v[134:135], v[138:139], 1.0 op_sel_hi:[1,1,0] neg_lo:[1,0,0] neg_hi:[1,0,0]
	v_pk_fma_f32 v[136:137], v[28:29], v[136:137], v[136:137]
	v_pk_fma_f32 v[138:139], v[30:31], v[138:139], v[138:139]
	v_div_fixup_f32 v136, v136, v132, 1.0
	v_div_fixup_f32 v137, v137, v133, 1.0
	v_div_fixup_f32 v138, v138, v134, 1.0
	v_div_fixup_f32 v139, v139, v135, 1.0
	v_pk_mul_f32 v[136:137], v[92:93], v[136:137]
	v_pk_mul_f32 v[138:139], v[94:95], v[138:139]
	v_cvt_pk_bf16_f32 v92, v136, v137
	v_cvt_pk_bf16_f32 v93, v138, v139
	ds_write_b64 v140, v[92:93] offset:112
	ds_read_b128 v[144:147], v141 offset:0
	ds_read_b128 v[148:151], v141 offset:1152
	ds_read_b128 v[152:155], v141 offset:2304
	ds_read_b128 v[156:159], v141 offset:3456
	s_waitcnt lgkmcnt(3)
	global_store_dwordx4 v142, v[144:147], s[6:7]
	v_add_u32_e32 v142, 0x2000, v142
	s_waitcnt lgkmcnt(2)
	global_store_dwordx4 v142, v[148:151], s[6:7]
	v_add_u32_e32 v142, 0x2000, v142
	s_waitcnt lgkmcnt(1)
	global_store_dwordx4 v142, v[152:155], s[6:7]
	v_add_u32_e32 v142, 0x2000, v142
	s_waitcnt lgkmcnt(0)
; DI float sigmoidf_(float x) { return 1.f / (1.f + __expf(-x)); }
; template <int WM>
; DI void inproj_tile(const Params& p, char* smem, const int m0, const int n0) {
;     ...
;   } else if (fw < 2304) {
;     if (WM == 4) {
;       const int blk = (fw - 1280) >> 7;
; #pragma unroll
;       for (int i = 0; i < 2; ++i)
; #pragma unroll
;         for (int j = 0; j < 2; ++j)
; #pragma unroll
;           for (int q4 = 0; q4 < 4; ++q4) {
;             const int ch = blk * 64 + i * 32 + q4 * 8 + hh * 4;
;             const size_t t = tb + j * 32;
;             float u[4];
; #pragma unroll
;             for (int z = 0; z < 4; ++z) u[z] = acc[i][j][q4 * 4 + z] * sigmoidf_(acc[(i + 2) & (WM - 1)][j][q4 * 4 + z]);
;             uint2 o;
;             o.x = pack2(u[0], u[1]);
;             o.y = pack2(u[2], u[3]);
;             *(uint2*)(GLU + t * 512 + ch) = o;
;           }
;     }
	global_store_dwordx4 v142, v[156:159], s[6:7]
	v_add_u32_e32 v142, 0x2000, v142
	v_pk_mul_f32 v[132:133], v[32:33], s[12:13] op_sel_hi:[1,0]
	v_pk_mul_f32 v[134:135], v[34:35], s[12:13] op_sel_hi:[1,0]
	v_exp_f32_e32 v132, v132
	v_exp_f32_e32 v133, v133
	v_exp_f32_e32 v134, v134
	v_exp_f32_e32 v135, v135
	v_pk_add_f32 v[132:133], v[132:133], 1.0 op_sel_hi:[1,0]
	v_pk_add_f32 v[134:135], v[134:135], 1.0 op_sel_hi:[1,0]
	v_rcp_f32_e32 v136, v132
	v_rcp_f32_e32 v137, v133
	v_rcp_f32_e32 v138, v134
	v_rcp_f32_e32 v139, v135
	v_pk_fma_f32 v[32:33], v[132:133], v[136:137], 1.0 op_sel_hi:[1,1,0] neg_lo:[1,0,0] neg_hi:[1,0,0]
	v_pk_fma_f32 v[34:35], v[134:135], v[138:139], 1.0 op_sel_hi:[1,1,0] neg_lo:[1,0,0] neg_hi:[1,0,0]
	v_pk_fma_f32 v[136:137], v[32:33], v[136:137], v[136:137]
	v_pk_fma_f32 v[138:139], v[34:35], v[138:139], v[138:139]
	v_div_fixup_f32 v136, v136, v132, 1.0
	v_div_fixup_f32 v137, v137, v133, 1.0
	v_div_fixup_f32 v138, v138, v134, 1.0
	v_div_fixup_f32 v139, v139, v135, 1.0
	v_pk_mul_f32 v[136:137], v[96:97], v[136:137]
	v_pk_mul_f32 v[138:139], v[98:99], v[138:139]
	v_cvt_pk_bf16_f32 v96, v136, v137
	v_cvt_pk_bf16_f32 v97, v138, v139
	ds_write_b64 v140, v[96:97] offset:4608
	v_pk_mul_f32 v[132:133], v[36:37], s[12:13] op_sel_hi:[1,0]
	v_pk_mul_f32 v[134:135], v[38:39], s[12:13] op_sel_hi:[1,0]
	v_exp_f32_e32 v132, v132
	v_exp_f32_e32 v133, v133
	v_exp_f32_e32 v134, v134
	v_exp_f32_e32 v135, v135
	v_pk_add_f32 v[132:133], v[132:133], 1.0 op_sel_hi:[1,0]
	v_pk_add_f32 v[134:135], v[134:135], 1.0 op_sel_hi:[1,0]
	v_rcp_f32_e32 v136, v132
	v_rcp_f32_e32 v137, v133
	v_rcp_f32_e32 v138, v134
	v_rcp_f32_e32 v139, v135
	v_pk_fma_f32 v[36:37], v[132:133], v[136:137], 1.0 op_sel_hi:[1,1,0] neg_lo:[1,0,0] neg_hi:[1,0,0]
	v_pk_fma_f32 v[38:39], v[134:135], v[138:139], 1.0 op_sel_hi:[1,1,0] neg_lo:[1,0,0] neg_hi:[1,0,0]
	v_pk_fma_f32 v[136:137], v[36:37], v[136:137], v[136:137]
	v_pk_fma_f32 v[138:139], v[38:39], v[138:139], v[138:139]
	v_div_fixup_f32 v136, v136, v132, 1.0
	v_div_fixup_f32 v137, v137, v133, 1.0
	v_div_fixup_f32 v138, v138, v134, 1.0
	v_div_fixup_f32 v139, v139, v135, 1.0
	v_pk_mul_f32 v[136:137], v[100:101], v[136:137]
	v_pk_mul_f32 v[138:139], v[102:103], v[138:139]
	v_cvt_pk_bf16_f32 v100, v136, v137
	v_cvt_pk_bf16_f32 v101, v138, v139
	ds_write_b64 v140, v[100:101] offset:4624
	v_pk_mul_f32 v[132:133], v[40:41], s[12:13] op_sel_hi:[1,0]
	v_pk_mul_f32 v[134:135], v[42:43], s[12:13] op_sel_hi:[1,0]
	v_exp_f32_e32 v132, v132
	v_exp_f32_e32 v133, v133
	v_exp_f32_e32 v134, v134
	v_exp_f32_e32 v135, v135
	v_pk_add_f32 v[132:133], v[132:133], 1.0 op_sel_hi:[1,0]
	v_pk_add_f32 v[134:135], v[134:135], 1.0 op_sel_hi:[1,0]
	v_rcp_f32_e32 v136, v132
	v_rcp_f32_e32 v137, v133
	v_rcp_f32_e32 v138, v134
	v_rcp_f32_e32 v139, v135
	v_pk_fma_f32 v[40:41], v[132:133], v[136:137], 1.0 op_sel_hi:[1,1,0] neg_lo:[1,0,0] neg_hi:[1,0,0]
	v_pk_fma_f32 v[42:43], v[134:135], v[138:139], 1.0 op_sel_hi:[1,1,0] neg_lo:[1,0,0] neg_hi:[1,0,0]
	v_pk_fma_f32 v[136:137], v[40:41], v[136:137], v[136:137]
	v_pk_fma_f32 v[138:139], v[42:43], v[138:139], v[138:139]
	v_div_fixup_f32 v136, v136, v132, 1.0
	v_div_fixup_f32 v137, v137, v133, 1.0
	v_div_fixup_f32 v138, v138, v134, 1.0
	v_div_fixup_f32 v139, v139, v135, 1.0
	v_pk_mul_f32 v[136:137], v[104:105], v[136:137]
	v_pk_mul_f32 v[138:139], v[106:107], v[138:139]
	v_cvt_pk_bf16_f32 v104, v136, v137
	v_cvt_pk_bf16_f32 v105, v138, v139
	ds_write_b64 v140, v[104:105] offset:4640
	v_pk_mul_f32 v[132:133], v[44:45], s[12:13] op_sel_hi:[1,0]
	v_pk_mul_f32 v[134:135], v[46:47], s[12:13] op_sel_hi:[1,0]
	v_exp_f32_e32 v132, v132
	v_exp_f32_e32 v133, v133
	v_exp_f32_e32 v134, v134
	v_exp_f32_e32 v135, v135
	v_pk_add_f32 v[132:133], v[132:133], 1.0 op_sel_hi:[1,0]
	v_pk_add_f32 v[134:135], v[134:135], 1.0 op_sel_hi:[1,0]
	v_rcp_f32_e32 v136, v132
	v_rcp_f32_e32 v137, v133
	v_rcp_f32_e32 v138, v134
	v_rcp_f32_e32 v139, v135
	v_pk_fma_f32 v[44:45], v[132:133], v[136:137], 1.0 op_sel_hi:[1,1,0] neg_lo:[1,0,0] neg_hi:[1,0,0]
	v_pk_fma_f32 v[46:47], v[134:135], v[138:139], 1.0 op_sel_hi:[1,1,0] neg_lo:[1,0,0] neg_hi:[1,0,0]
	v_pk_fma_f32 v[136:137], v[44:45], v[136:137], v[136:137]
	v_pk_fma_f32 v[138:139], v[46:47], v[138:139], v[138:139]
	v_div_fixup_f32 v136, v136, v132, 1.0
	v_div_fixup_f32 v137, v137, v133, 1.0
	v_div_fixup_f32 v138, v138, v134, 1.0
	v_div_fixup_f32 v139, v139, v135, 1.0
	v_pk_mul_f32 v[136:137], v[108:109], v[136:137]
	v_pk_mul_f32 v[138:139], v[110:111], v[138:139]
	v_cvt_pk_bf16_f32 v108, v136, v137
	v_cvt_pk_bf16_f32 v109, v138, v139
	ds_write_b64 v140, v[108:109] offset:4656
	v_pk_mul_f32 v[132:133], v[0:1], s[12:13] op_sel_hi:[1,0]
	v_pk_mul_f32 v[134:135], v[2:3], s[12:13] op_sel_hi:[1,0]
	v_exp_f32_e32 v132, v132
	v_exp_f32_e32 v133, v133
	v_exp_f32_e32 v134, v134
	v_exp_f32_e32 v135, v135
; DI float sigmoidf_(float x) { return 1.f / (1.f + __expf(-x)); }
; template <int WM>
; DI void inproj_tile(const Params& p, char* smem, const int m0, const int n0) {
;     ...
;   } else if (fw < 2304) {
;     if (WM == 4) {
;       const int blk = (fw - 1280) >> 7;
; #pragma unroll
;       for (int i = 0; i < 2; ++i)
; #pragma unroll
;         for (int j = 0; j < 2; ++j)
; #pragma unroll
;           for (int q4 = 0; q4 < 4; ++q4) {
;             const int ch = blk * 64 + i * 32 + q4 * 8 + hh * 4;
;             const size_t t = tb + j * 32;
;             float u[4];
; #pragma unroll
;             for (int z = 0; z < 4; ++z) u[z] = acc[i][j][q4 * 4 + z] * sigmoidf_(acc[(i + 2) & (WM - 1)][j][q4 * 4 + z]);
;             uint2 o;
;             o.x = pack2(u[0], u[1]);
;             o.y = pack2(u[2], u[3]);
;             *(uint2*)(GLU + t * 512 + ch) = o;
;           }
;     }
	v_pk_add_f32 v[132:133], v[132:133], 1.0 op_sel_hi:[1,0]
	v_pk_add_f32 v[134:135], v[134:135], 1.0 op_sel_hi:[1,0]
	v_rcp_f32_e32 v136, v132
	v_rcp_f32_e32 v137, v133
	v_rcp_f32_e32 v138, v134
	v_rcp_f32_e32 v139, v135
	v_pk_fma_f32 v[0:1], v[132:133], v[136:137], 1.0 op_sel_hi:[1,1,0] neg_lo:[1,0,0] neg_hi:[1,0,0]
	v_pk_fma_f32 v[2:3], v[134:135], v[138:139], 1.0 op_sel_hi:[1,1,0] neg_lo:[1,0,0] neg_hi:[1,0,0]
	v_pk_fma_f32 v[136:137], v[0:1], v[136:137], v[136:137]
	v_pk_fma_f32 v[138:139], v[2:3], v[138:139], v[138:139]
	v_div_fixup_f32 v136, v136, v132, 1.0
	v_div_fixup_f32 v137, v137, v133, 1.0
	v_div_fixup_f32 v138, v138, v134, 1.0
	v_div_fixup_f32 v139, v139, v135, 1.0
	v_pk_mul_f32 v[136:137], v[64:65], v[136:137]
	v_pk_mul_f32 v[138:139], v[66:67], v[138:139]
	v_cvt_pk_bf16_f32 v64, v136, v137
	v_cvt_pk_bf16_f32 v65, v138, v139
	ds_write_b64 v140, v[64:65] offset:4672
	v_pk_mul_f32 v[132:133], v[4:5], s[12:13] op_sel_hi:[1,0]
	v_pk_mul_f32 v[134:135], v[6:7], s[12:13] op_sel_hi:[1,0]
	v_exp_f32_e32 v132, v132
	v_exp_f32_e32 v133, v133
	v_exp_f32_e32 v134, v134
	v_exp_f32_e32 v135, v135
	v_pk_add_f32 v[132:133], v[132:133], 1.0 op_sel_hi:[1,0]
	v_pk_add_f32 v[134:135], v[134:135], 1.0 op_sel_hi:[1,0]
	v_rcp_f32_e32 v136, v132
	v_rcp_f32_e32 v137, v133
	v_rcp_f32_e32 v138, v134
	v_rcp_f32_e32 v139, v135
	v_pk_fma_f32 v[4:5], v[132:133], v[136:137], 1.0 op_sel_hi:[1,1,0] neg_lo:[1,0,0] neg_hi:[1,0,0]
	v_pk_fma_f32 v[6:7], v[134:135], v[138:139], 1.0 op_sel_hi:[1,1,0] neg_lo:[1,0,0] neg_hi:[1,0,0]
	v_pk_fma_f32 v[136:137], v[4:5], v[136:137], v[136:137]
	v_pk_fma_f32 v[138:139], v[6:7], v[138:139], v[138:139]
	v_div_fixup_f32 v136, v136, v132, 1.0
	v_div_fixup_f32 v137, v137, v133, 1.0
	v_div_fixup_f32 v138, v138, v134, 1.0
	v_div_fixup_f32 v139, v139, v135, 1.0
	v_pk_mul_f32 v[136:137], v[68:69], v[136:137]
	v_pk_mul_f32 v[138:139], v[70:71], v[138:139]
	v_cvt_pk_bf16_f32 v68, v136, v137
	v_cvt_pk_bf16_f32 v69, v138, v139
	ds_write_b64 v140, v[68:69] offset:4688
	v_pk_mul_f32 v[132:133], v[8:9], s[12:13] op_sel_hi:[1,0]
	v_pk_mul_f32 v[134:135], v[10:11], s[12:13] op_sel_hi:[1,0]
	v_exp_f32_e32 v132, v132
	v_exp_f32_e32 v133, v133
	v_exp_f32_e32 v134, v134
	v_exp_f32_e32 v135, v135
	v_pk_add_f32 v[132:133], v[132:133], 1.0 op_sel_hi:[1,0]
	v_pk_add_f32 v[134:135], v[134:135], 1.0 op_sel_hi:[1,0]
	v_rcp_f32_e32 v136, v132
	v_rcp_f32_e32 v137, v133
	v_rcp_f32_e32 v138, v134
	v_rcp_f32_e32 v139, v135
	v_pk_fma_f32 v[8:9], v[132:133], v[136:137], 1.0 op_sel_hi:[1,1,0] neg_lo:[1,0,0] neg_hi:[1,0,0]
	v_pk_fma_f32 v[10:11], v[134:135], v[138:139], 1.0 op_sel_hi:[1,1,0] neg_lo:[1,0,0] neg_hi:[1,0,0]
	v_pk_fma_f32 v[136:137], v[8:9], v[136:137], v[136:137]
	v_pk_fma_f32 v[138:139], v[10:11], v[138:139], v[138:139]
	v_div_fixup_f32 v136, v136, v132, 1.0
	v_div_fixup_f32 v137, v137, v133, 1.0
	v_div_fixup_f32 v138, v138, v134, 1.0
	v_div_fixup_f32 v139, v139, v135, 1.0
	v_pk_mul_f32 v[136:137], v[72:73], v[136:137]
	v_pk_mul_f32 v[138:139], v[74:75], v[138:139]
	v_cvt_pk_bf16_f32 v72, v136, v137
	v_cvt_pk_bf16_f32 v73, v138, v139
	ds_write_b64 v140, v[72:73] offset:4704
	v_pk_mul_f32 v[132:133], v[12:13], s[12:13] op_sel_hi:[1,0]
	v_pk_mul_f32 v[134:135], v[14:15], s[12:13] op_sel_hi:[1,0]
	v_exp_f32_e32 v132, v132
	v_exp_f32_e32 v133, v133
	v_exp_f32_e32 v134, v134
	v_exp_f32_e32 v135, v135
	v_pk_add_f32 v[132:133], v[132:133], 1.0 op_sel_hi:[1,0]
	v_pk_add_f32 v[134:135], v[134:135], 1.0 op_sel_hi:[1,0]
	v_rcp_f32_e32 v136, v132
	v_rcp_f32_e32 v137, v133
	v_rcp_f32_e32 v138, v134
	v_rcp_f32_e32 v139, v135
	v_pk_fma_f32 v[12:13], v[132:133], v[136:137], 1.0 op_sel_hi:[1,1,0] neg_lo:[1,0,0] neg_hi:[1,0,0]
	v_pk_fma_f32 v[14:15], v[134:135], v[138:139], 1.0 op_sel_hi:[1,1,0] neg_lo:[1,0,0] neg_hi:[1,0,0]
	v_pk_fma_f32 v[136:137], v[12:13], v[136:137], v[136:137]
	v_pk_fma_f32 v[138:139], v[14:15], v[138:139], v[138:139]
	v_div_fixup_f32 v136, v136, v132, 1.0
	v_div_fixup_f32 v137, v137, v133, 1.0
	v_div_fixup_f32 v138, v138, v134, 1.0
	v_div_fixup_f32 v139, v139, v135, 1.0
	v_pk_mul_f32 v[136:137], v[76:77], v[136:137]
	v_pk_mul_f32 v[138:139], v[78:79], v[138:139]
	v_cvt_pk_bf16_f32 v76, v136, v137
	v_cvt_pk_bf16_f32 v77, v138, v139
	ds_write_b64 v140, v[76:77] offset:4720
	ds_read_b128 v[144:147], v141 offset:4608
	ds_read_b128 v[148:151], v141 offset:5760
	ds_read_b128 v[152:155], v141 offset:6912
	ds_read_b128 v[156:159], v141 offset:8064
	s_waitcnt lgkmcnt(3)
	global_store_dwordx4 v142, v[144:147], s[6:7]
	v_add_u32_e32 v142, 0x2000, v142
	s_waitcnt lgkmcnt(2)
	global_store_dwordx4 v142, v[148:151], s[6:7]
	v_add_u32_e32 v142, 0x2000, v142
	s_waitcnt lgkmcnt(1)
	global_store_dwordx4 v142, v[152:155], s[6:7]
	v_add_u32_e32 v142, 0x2000, v142
	s_waitcnt lgkmcnt(0)
	global_store_dwordx4 v142, v[156:159], s[6:7]
	v_add_u32_e32 v142, 0x2000, v142

; template <int WM>
; DI void inproj_tile(const Params& p, char* smem, const int m0, const int n0) {
;     ...
;   if (fw < 512) {
; #pragma unroll
;     for (int i = 0; i < WM; ++i)
; #pragma unroll
;       for (int j = 0; j < 2; ++j)
; #pragma unroll
;         for (int q4 = 0; q4 < 4; ++q4) {
;           const int f = fw + i * 32 + q4 * 8 + hh * 4;
;           const size_t t = tb + j * 32;
;           const float sc = 0.125f * LOG2E;
;           uint2 o;
;           o.x = pack2(acc[i][j][q4 * 4 + 0] * sc, acc[i][j][q4 * 4 + 1] * sc);
;           o.y = pack2(acc[i][j][q4 * 4 + 2] * sc, acc[i][j][q4 * 4 + 3] * sc);
;           *(uint2*)(Q + t * 512 + f) = o;
;         }
.LBB0_190:
	s_waitcnt vmcnt(0)
	v_mbcnt_lo_u32_b32 v143, -1, 0
	v_mbcnt_hi_u32_b32 v143, -1, v143
	v_lshrrev_b32_e32 v132, 6, v211
	v_mul_u32_u24_e32 v132, 17408, v132
	v_and_b32_e32 v133, 31, v143
	v_lshrrev_b32_e32 v134, 5, v143
	v_mul_u32_u24_e32 v133, 272, v133
	v_lshl_add_u32 v133, v134, 3, v133
	v_add3_u32 v140, v133, v132, 64
	v_lshrrev_b32_e32 v135, 4, v143
	v_and_b32_e32 v136, 15, v143
	v_mul_u32_u24_e32 v137, 272, v135
	v_lshl_add_u32 v137, v136, 4, v137
	v_add3_u32 v141, v137, v132, 64
	v_and_b32_e32 v138, 0xffffffe0, v129
	v_add_u32_e32 v138, v138, v135
	v_lshlrev_b32_e32 v138, 10, v138
	v_mov_b32_e32 v139, v131
	v_lshl_add_u32 v138, v139, 1, v138
	v_lshl_add_u32 v142, v136, 4, v138
	v_pk_mul_f32 v[136:137], v[112:113], s[16:17] op_sel_hi:[1,0]
	v_pk_mul_f32 v[138:139], v[114:115], s[16:17] op_sel_hi:[1,0]
	v_cvt_pk_bf16_f32 v112, v136, v137
	v_cvt_pk_bf16_f32 v113, v138, v139
	ds_write_b64 v140, v[112:113] offset:0
	v_pk_mul_f32 v[136:137], v[116:117], s[16:17] op_sel_hi:[1,0]
	v_pk_mul_f32 v[138:139], v[118:119], s[16:17] op_sel_hi:[1,0]
	v_cvt_pk_bf16_f32 v116, v136, v137
	v_cvt_pk_bf16_f32 v117, v138, v139
	ds_write_b64 v140, v[116:117] offset:16
	v_pk_mul_f32 v[136:137], v[120:121], s[16:17] op_sel_hi:[1,0]
	v_pk_mul_f32 v[138:139], v[122:123], s[16:17] op_sel_hi:[1,0]
	v_cvt_pk_bf16_f32 v120, v136, v137
	v_cvt_pk_bf16_f32 v121, v138, v139
	ds_write_b64 v140, v[120:121] offset:32
	v_pk_mul_f32 v[136:137], v[124:125], s[16:17] op_sel_hi:[1,0]
	v_pk_mul_f32 v[138:139], v[126:127], s[16:17] op_sel_hi:[1,0]
	v_cvt_pk_bf16_f32 v124, v136, v137
	v_cvt_pk_bf16_f32 v125, v138, v139
	ds_write_b64 v140, v[124:125] offset:48
	v_pk_mul_f32 v[136:137], v[80:81], s[16:17] op_sel_hi:[1,0]
	v_pk_mul_f32 v[138:139], v[82:83], s[16:17] op_sel_hi:[1,0]
	v_cvt_pk_bf16_f32 v80, v136, v137
	v_cvt_pk_bf16_f32 v81, v138, v139
	ds_write_b64 v140, v[80:81] offset:64
	v_pk_mul_f32 v[136:137], v[84:85], s[16:17] op_sel_hi:[1,0]
	v_pk_mul_f32 v[138:139], v[86:87], s[16:17] op_sel_hi:[1,0]
	v_cvt_pk_bf16_f32 v84, v136, v137
	v_cvt_pk_bf16_f32 v85, v138, v139
	ds_write_b64 v140, v[84:85] offset:80
	v_pk_mul_f32 v[136:137], v[88:89], s[16:17] op_sel_hi:[1,0]
	v_pk_mul_f32 v[138:139], v[90:91], s[16:17] op_sel_hi:[1,0]
	v_cvt_pk_bf16_f32 v88, v136, v137
	v_cvt_pk_bf16_f32 v89, v138, v139
	ds_write_b64 v140, v[88:89] offset:96
	v_pk_mul_f32 v[136:137], v[92:93], s[16:17] op_sel_hi:[1,0]
	v_pk_mul_f32 v[138:139], v[94:95], s[16:17] op_sel_hi:[1,0]
	v_cvt_pk_bf16_f32 v92, v136, v137
	v_cvt_pk_bf16_f32 v93, v138, v139
	ds_write_b64 v140, v[92:93] offset:112
	v_pk_mul_f32 v[136:137], v[48:49], s[16:17] op_sel_hi:[1,0]
	v_pk_mul_f32 v[138:139], v[50:51], s[16:17] op_sel_hi:[1,0]
	v_cvt_pk_bf16_f32 v48, v136, v137
	v_cvt_pk_bf16_f32 v49, v138, v139
	ds_write_b64 v140, v[48:49] offset:128
	v_pk_mul_f32 v[136:137], v[52:53], s[16:17] op_sel_hi:[1,0]
	v_pk_mul_f32 v[138:139], v[54:55], s[16:17] op_sel_hi:[1,0]
	v_cvt_pk_bf16_f32 v52, v136, v137
	v_cvt_pk_bf16_f32 v53, v138, v139
	ds_write_b64 v140, v[52:53] offset:144
	v_pk_mul_f32 v[136:137], v[56:57], s[16:17] op_sel_hi:[1,0]
	v_pk_mul_f32 v[138:139], v[58:59], s[16:17] op_sel_hi:[1,0]
	v_cvt_pk_bf16_f32 v56, v136, v137
	v_cvt_pk_bf16_f32 v57, v138, v139
	ds_write_b64 v140, v[56:57] offset:160
	v_pk_mul_f32 v[136:137], v[60:61], s[16:17] op_sel_hi:[1,0]
	v_pk_mul_f32 v[138:139], v[62:63], s[16:17] op_sel_hi:[1,0]
	v_cvt_pk_bf16_f32 v60, v136, v137
	v_cvt_pk_bf16_f32 v61, v138, v139
	ds_write_b64 v140, v[60:61] offset:176
	v_pk_mul_f32 v[136:137], v[16:17], s[16:17] op_sel_hi:[1,0]
	v_pk_mul_f32 v[138:139], v[18:19], s[16:17] op_sel_hi:[1,0]
	v_cvt_pk_bf16_f32 v16, v136, v137
	v_cvt_pk_bf16_f32 v17, v138, v139
	ds_write_b64 v140, v[16:17] offset:192
	v_pk_mul_f32 v[136:137], v[20:21], s[16:17] op_sel_hi:[1,0]
	v_pk_mul_f32 v[138:139], v[22:23], s[16:17] op_sel_hi:[1,0]
	v_cvt_pk_bf16_f32 v20, v136, v137
	v_cvt_pk_bf16_f32 v21, v138, v139
	ds_write_b64 v140, v[20:21] offset:208
	v_pk_mul_f32 v[136:137], v[24:25], s[16:17] op_sel_hi:[1,0]
	v_pk_mul_f32 v[138:139], v[26:27], s[16:17] op_sel_hi:[1,0]
	v_cvt_pk_bf16_f32 v24, v136, v137
	v_cvt_pk_bf16_f32 v25, v138, v139
	ds_write_b64 v140, v[24:25] offset:224
	v_pk_mul_f32 v[136:137], v[28:29], s[16:17] op_sel_hi:[1,0]
	v_pk_mul_f32 v[138:139], v[30:31], s[16:17] op_sel_hi:[1,0]
	v_cvt_pk_bf16_f32 v28, v136, v137
	v_cvt_pk_bf16_f32 v29, v138, v139
	ds_write_b64 v140, v[28:29] offset:240
	ds_read_b128 v[144:147], v141 offset:0
	ds_read_b128 v[148:151], v141 offset:1088
	ds_read_b128 v[152:155], v141 offset:2176
	ds_read_b128 v[156:159], v141 offset:3264
	ds_read_b128 v[160:163], v141 offset:4352
	ds_read_b128 v[168:171], v141 offset:5440
	ds_read_b128 v[172:175], v141 offset:6528
	ds_read_b128 v[176:179], v141 offset:7616
	s_waitcnt lgkmcnt(7)
	global_store_dwordx4 v142, v[144:147], s[4:5]
	v_add_u32_e32 v142, 0x1000, v142
	s_waitcnt lgkmcnt(6)
	global_store_dwordx4 v142, v[148:151], s[4:5]
	v_add_u32_e32 v142, 0x1000, v142
	s_waitcnt lgkmcnt(5)
	global_store_dwordx4 v142, v[152:155], s[4:5]
	v_add_u32_e32 v142, 0x1000, v142
	s_waitcnt lgkmcnt(4)
	global_store_dwordx4 v142, v[156:159], s[4:5]
	v_add_u32_e32 v142, 0x1000, v142
	s_waitcnt lgkmcnt(3)
; template <int WM>
; DI void inproj_tile(const Params& p, char* smem, const int m0, const int n0) {
;     ...
;   if (fw < 512) {
; #pragma unroll
;     for (int i = 0; i < WM; ++i)
; #pragma unroll
;       for (int j = 0; j < 2; ++j)
; #pragma unroll
;         for (int q4 = 0; q4 < 4; ++q4) {
;           const int f = fw + i * 32 + q4 * 8 + hh * 4;
;           const size_t t = tb + j * 32;
;           const float sc = 0.125f * LOG2E;
;           uint2 o;
;           o.x = pack2(acc[i][j][q4 * 4 + 0] * sc, acc[i][j][q4 * 4 + 1] * sc);
;           o.y = pack2(acc[i][j][q4 * 4 + 2] * sc, acc[i][j][q4 * 4 + 3] * sc);
;           *(uint2*)(Q + t * 512 + f) = o;
;         }
	global_store_dwordx4 v142, v[160:163], s[4:5]
	v_add_u32_e32 v142, 0x1000, v142
	s_waitcnt lgkmcnt(2)
	global_store_dwordx4 v142, v[168:171], s[4:5]
	v_add_u32_e32 v142, 0x1000, v142
	s_waitcnt lgkmcnt(1)
	global_store_dwordx4 v142, v[172:175], s[4:5]
	v_add_u32_e32 v142, 0x1000, v142
	s_waitcnt lgkmcnt(0)
	global_store_dwordx4 v142, v[176:179], s[4:5]
	v_add_u32_e32 v142, 0x1000, v142
	v_pk_mul_f32 v[136:137], v[96:97], s[16:17] op_sel_hi:[1,0]
	v_pk_mul_f32 v[138:139], v[98:99], s[16:17] op_sel_hi:[1,0]
	v_cvt_pk_bf16_f32 v96, v136, v137
	v_cvt_pk_bf16_f32 v97, v138, v139
	ds_write_b64 v140, v[96:97] offset:8704
	v_pk_mul_f32 v[136:137], v[100:101], s[16:17] op_sel_hi:[1,0]
	v_pk_mul_f32 v[138:139], v[102:103], s[16:17] op_sel_hi:[1,0]
	v_cvt_pk_bf16_f32 v100, v136, v137
	v_cvt_pk_bf16_f32 v101, v138, v139
	ds_write_b64 v140, v[100:101] offset:8720
	v_pk_mul_f32 v[136:137], v[104:105], s[16:17] op_sel_hi:[1,0]
	v_pk_mul_f32 v[138:139], v[106:107], s[16:17] op_sel_hi:[1,0]
	v_cvt_pk_bf16_f32 v104, v136, v137
	v_cvt_pk_bf16_f32 v105, v138, v139
	ds_write_b64 v140, v[104:105] offset:8736
	v_pk_mul_f32 v[136:137], v[108:109], s[16:17] op_sel_hi:[1,0]
	v_pk_mul_f32 v[138:139], v[110:111], s[16:17] op_sel_hi:[1,0]
	v_cvt_pk_bf16_f32 v108, v136, v137
	v_cvt_pk_bf16_f32 v109, v138, v139
	ds_write_b64 v140, v[108:109] offset:8752
	v_pk_mul_f32 v[136:137], v[64:65], s[16:17] op_sel_hi:[1,0]
	v_pk_mul_f32 v[138:139], v[66:67], s[16:17] op_sel_hi:[1,0]
	v_cvt_pk_bf16_f32 v64, v136, v137
	v_cvt_pk_bf16_f32 v65, v138, v139
	ds_write_b64 v140, v[64:65] offset:8768
	v_pk_mul_f32 v[136:137], v[68:69], s[16:17] op_sel_hi:[1,0]
	v_pk_mul_f32 v[138:139], v[70:71], s[16:17] op_sel_hi:[1,0]
	v_cvt_pk_bf16_f32 v68, v136, v137
	v_cvt_pk_bf16_f32 v69, v138, v139
	ds_write_b64 v140, v[68:69] offset:8784
	v_pk_mul_f32 v[136:137], v[72:73], s[16:17] op_sel_hi:[1,0]
	v_pk_mul_f32 v[138:139], v[74:75], s[16:17] op_sel_hi:[1,0]
	v_cvt_pk_bf16_f32 v72, v136, v137
	v_cvt_pk_bf16_f32 v73, v138, v139
	ds_write_b64 v140, v[72:73] offset:8800
	v_pk_mul_f32 v[136:137], v[76:77], s[16:17] op_sel_hi:[1,0]
	v_pk_mul_f32 v[138:139], v[78:79], s[16:17] op_sel_hi:[1,0]
	v_cvt_pk_bf16_f32 v76, v136, v137
	v_cvt_pk_bf16_f32 v77, v138, v139
	ds_write_b64 v140, v[76:77] offset:8816
	v_pk_mul_f32 v[136:137], v[32:33], s[16:17] op_sel_hi:[1,0]
	v_pk_mul_f32 v[138:139], v[34:35], s[16:17] op_sel_hi:[1,0]
	v_cvt_pk_bf16_f32 v32, v136, v137
	v_cvt_pk_bf16_f32 v33, v138, v139
	ds_write_b64 v140, v[32:33] offset:8832
	v_pk_mul_f32 v[136:137], v[36:37], s[16:17] op_sel_hi:[1,0]
	v_pk_mul_f32 v[138:139], v[38:39], s[16:17] op_sel_hi:[1,0]
	v_cvt_pk_bf16_f32 v36, v136, v137
	v_cvt_pk_bf16_f32 v37, v138, v139
	ds_write_b64 v140, v[36:37] offset:8848
	v_pk_mul_f32 v[136:137], v[40:41], s[16:17] op_sel_hi:[1,0]
	v_pk_mul_f32 v[138:139], v[42:43], s[16:17] op_sel_hi:[1,0]
	v_cvt_pk_bf16_f32 v40, v136, v137
	v_cvt_pk_bf16_f32 v41, v138, v139
	ds_write_b64 v140, v[40:41] offset:8864
	v_pk_mul_f32 v[136:137], v[44:45], s[16:17] op_sel_hi:[1,0]
	v_pk_mul_f32 v[138:139], v[46:47], s[16:17] op_sel_hi:[1,0]
	v_cvt_pk_bf16_f32 v44, v136, v137
	v_cvt_pk_bf16_f32 v45, v138, v139
	ds_write_b64 v140, v[44:45] offset:8880
	v_pk_mul_f32 v[136:137], v[0:1], s[16:17] op_sel_hi:[1,0]
	v_pk_mul_f32 v[138:139], v[2:3], s[16:17] op_sel_hi:[1,0]
	v_cvt_pk_bf16_f32 v0, v136, v137
	v_cvt_pk_bf16_f32 v1, v138, v139
	ds_write_b64 v140, v[0:1] offset:8896
	v_pk_mul_f32 v[136:137], v[4:5], s[16:17] op_sel_hi:[1,0]
	v_pk_mul_f32 v[138:139], v[6:7], s[16:17] op_sel_hi:[1,0]
	v_cvt_pk_bf16_f32 v4, v136, v137
	v_cvt_pk_bf16_f32 v5, v138, v139
	ds_write_b64 v140, v[4:5] offset:8912
	v_pk_mul_f32 v[136:137], v[8:9], s[16:17] op_sel_hi:[1,0]
	v_pk_mul_f32 v[138:139], v[10:11], s[16:17] op_sel_hi:[1,0]
	v_cvt_pk_bf16_f32 v8, v136, v137
	v_cvt_pk_bf16_f32 v9, v138, v139
	ds_write_b64 v140, v[8:9] offset:8928
	v_pk_mul_f32 v[136:137], v[12:13], s[16:17] op_sel_hi:[1,0]
	v_pk_mul_f32 v[138:139], v[14:15], s[16:17] op_sel_hi:[1,0]
	v_cvt_pk_bf16_f32 v12, v136, v137
	v_cvt_pk_bf16_f32 v13, v138, v139
	ds_write_b64 v140, v[12:13] offset:8944
	ds_read_b128 v[144:147], v141 offset:8704
	ds_read_b128 v[148:151], v141 offset:9792
	ds_read_b128 v[152:155], v141 offset:10880
	ds_read_b128 v[156:159], v141 offset:11968
	ds_read_b128 v[160:163], v141 offset:13056
	ds_read_b128 v[168:171], v141 offset:14144
	ds_read_b128 v[172:175], v141 offset:15232
	ds_read_b128 v[176:179], v141 offset:16320
	s_waitcnt lgkmcnt(7)
	global_store_dwordx4 v142, v[144:147], s[4:5]
	v_add_u32_e32 v142, 0x1000, v142
	s_waitcnt lgkmcnt(6)
	global_store_dwordx4 v142, v[148:151], s[4:5]
	v_add_u32_e32 v142, 0x1000, v142
	s_waitcnt lgkmcnt(5)
	global_store_dwordx4 v142, v[152:155], s[4:5]
	v_add_u32_e32 v142, 0x1000, v142
	s_waitcnt lgkmcnt(4)
	global_store_dwordx4 v142, v[156:159], s[4:5]
	v_add_u32_e32 v142, 0x1000, v142
	s_waitcnt lgkmcnt(3)
	global_store_dwordx4 v142, v[160:163], s[4:5]
	v_add_u32_e32 v142, 0x1000, v142
	s_waitcnt lgkmcnt(2)
	global_store_dwordx4 v142, v[168:171], s[4:5]
	v_add_u32_e32 v142, 0x1000, v142
	s_waitcnt lgkmcnt(1)
	global_store_dwordx4 v142, v[172:175], s[4:5]
	v_add_u32_e32 v142, 0x1000, v142
	s_waitcnt lgkmcnt(0)
	global_store_dwordx4 v142, v[176:179], s[4:5]
	v_add_u32_e32 v142, 0x1000, v142
	s_branch .LBB0_164

; DI float sigmoidf_(float x) { return 1.f / (1.f + __expf(-x)); }
; template <int WM>
; DI void inproj_tile(const Params& p, char* smem, const int m0, const int n0) {
;     ...
;   } else if (fw < 4352) {
; #pragma unroll
;     for (int i = 0; i < WM; ++i)
; #pragma unroll
;       for (int j = 0; j < 2; ++j)
; #pragma unroll
;         for (int q4 = 0; q4 < 4; ++q4) {
;           const int f = fw - 2304 + i * 32 + q4 * 8 + hh * 4;
;           const size_t t = tb + j * 32;
;           uint2 o;
;           o.x = pack2(sigmoidf_(acc[i][j][q4 * 4 + 0]), sigmoidf_(acc[i][j][q4 * 4 + 1]));
;           o.y = pack2(sigmoidf_(acc[i][j][q4 * 4 + 2]), sigmoidf_(acc[i][j][q4 * 4 + 3]));
;           *(uint2*)(MG + t * 2048 + f) = o;
;         }
.LBB0_200:
	s_andn2_saveexec_b64 s[10:11], s[12:13]
	s_cbranch_execz .LBB0_202
	s_waitcnt vmcnt(0)
	v_mbcnt_lo_u32_b32 v143, -1, 0
	v_mbcnt_hi_u32_b32 v143, -1, v143
	v_lshrrev_b32_e32 v132, 6, v211
	v_mul_u32_u24_e32 v132, 9216, v132
	v_and_b32_e32 v133, 31, v143
	v_lshrrev_b32_e32 v134, 5, v143
	v_mul_u32_u24_e32 v133, 144, v133
	v_lshl_add_u32 v133, v134, 3, v133
	v_add3_u32 v140, v133, v132, 64
	v_lshrrev_b32_e32 v135, 3, v143
	v_and_b32_e32 v136, 7, v143
	v_mul_u32_u24_e32 v137, 144, v135
	v_lshl_add_u32 v137, v136, 4, v137
	v_add3_u32 v141, v137, v132, 64
	v_and_b32_e32 v138, 0xffffffe0, v64
	v_add_u32_e32 v138, v138, v135
	v_lshlrev_b32_e32 v138, 12, v138
	v_add_u32_e32 v139, 4294964992, v66
	v_lshl_add_u32 v138, v139, 1, v138
	v_lshl_add_u32 v142, v136, 4, v138
	s_mov_b32 s12, 0xbfb8aa3b
	v_pk_mul_f32 v[132:133], v[48:49], s[12:13] op_sel_hi:[1,0]
	v_pk_mul_f32 v[134:135], v[50:51], s[12:13] op_sel_hi:[1,0]
	v_exp_f32_e32 v132, v132
	v_exp_f32_e32 v133, v133
	v_exp_f32_e32 v134, v134
	v_exp_f32_e32 v135, v135
	v_pk_add_f32 v[132:133], v[132:133], 1.0 op_sel_hi:[1,0]
	v_pk_add_f32 v[134:135], v[134:135], 1.0 op_sel_hi:[1,0]
	v_rcp_f32_e32 v136, v132
	v_rcp_f32_e32 v137, v133
	v_rcp_f32_e32 v138, v134
	v_rcp_f32_e32 v139, v135
	v_pk_fma_f32 v[48:49], v[132:133], v[136:137], 1.0 op_sel_hi:[1,1,0] neg_lo:[1,0,0] neg_hi:[1,0,0]
	v_pk_fma_f32 v[50:51], v[134:135], v[138:139], 1.0 op_sel_hi:[1,1,0] neg_lo:[1,0,0] neg_hi:[1,0,0]
	v_pk_fma_f32 v[136:137], v[48:49], v[136:137], v[136:137]
	v_pk_fma_f32 v[138:139], v[50:51], v[138:139], v[138:139]
	v_div_fixup_f32 v136, v136, v132, 1.0
	v_div_fixup_f32 v137, v137, v133, 1.0
	v_div_fixup_f32 v138, v138, v134, 1.0
	v_div_fixup_f32 v139, v139, v135, 1.0
	v_cvt_pk_bf16_f32 v48, v136, v137
	v_cvt_pk_bf16_f32 v49, v138, v139
	ds_write_b64 v140, v[48:49] offset:0
	v_pk_mul_f32 v[132:133], v[52:53], s[12:13] op_sel_hi:[1,0]
	v_pk_mul_f32 v[134:135], v[54:55], s[12:13] op_sel_hi:[1,0]
	v_exp_f32_e32 v132, v132
	v_exp_f32_e32 v133, v133
	v_exp_f32_e32 v134, v134
	v_exp_f32_e32 v135, v135
	v_pk_add_f32 v[132:133], v[132:133], 1.0 op_sel_hi:[1,0]
	v_pk_add_f32 v[134:135], v[134:135], 1.0 op_sel_hi:[1,0]
	v_rcp_f32_e32 v136, v132
	v_rcp_f32_e32 v137, v133
	v_rcp_f32_e32 v138, v134
	v_rcp_f32_e32 v139, v135
	v_pk_fma_f32 v[52:53], v[132:133], v[136:137], 1.0 op_sel_hi:[1,1,0] neg_lo:[1,0,0] neg_hi:[1,0,0]
	v_pk_fma_f32 v[54:55], v[134:135], v[138:139], 1.0 op_sel_hi:[1,1,0] neg_lo:[1,0,0] neg_hi:[1,0,0]
	v_pk_fma_f32 v[136:137], v[52:53], v[136:137], v[136:137]
	v_pk_fma_f32 v[138:139], v[54:55], v[138:139], v[138:139]
	v_div_fixup_f32 v136, v136, v132, 1.0
	v_div_fixup_f32 v137, v137, v133, 1.0
	v_div_fixup_f32 v138, v138, v134, 1.0
	v_div_fixup_f32 v139, v139, v135, 1.0
	v_cvt_pk_bf16_f32 v52, v136, v137
	v_cvt_pk_bf16_f32 v53, v138, v139
	ds_write_b64 v140, v[52:53] offset:16
	v_pk_mul_f32 v[132:133], v[56:57], s[12:13] op_sel_hi:[1,0]
	v_pk_mul_f32 v[134:135], v[58:59], s[12:13] op_sel_hi:[1,0]
	v_exp_f32_e32 v132, v132
	v_exp_f32_e32 v133, v133
	v_exp_f32_e32 v134, v134
	v_exp_f32_e32 v135, v135
	v_pk_add_f32 v[132:133], v[132:133], 1.0 op_sel_hi:[1,0]
	v_pk_add_f32 v[134:135], v[134:135], 1.0 op_sel_hi:[1,0]
	v_rcp_f32_e32 v136, v132
	v_rcp_f32_e32 v137, v133
	v_rcp_f32_e32 v138, v134
	v_rcp_f32_e32 v139, v135
	v_pk_fma_f32 v[56:57], v[132:133], v[136:137], 1.0 op_sel_hi:[1,1,0] neg_lo:[1,0,0] neg_hi:[1,0,0]
	v_pk_fma_f32 v[58:59], v[134:135], v[138:139], 1.0 op_sel_hi:[1,1,0] neg_lo:[1,0,0] neg_hi:[1,0,0]
	v_pk_fma_f32 v[136:137], v[56:57], v[136:137], v[136:137]
	v_pk_fma_f32 v[138:139], v[58:59], v[138:139], v[138:139]
	v_div_fixup_f32 v136, v136, v132, 1.0
	v_div_fixup_f32 v137, v137, v133, 1.0
	v_div_fixup_f32 v138, v138, v134, 1.0
	v_div_fixup_f32 v139, v139, v135, 1.0
	v_cvt_pk_bf16_f32 v56, v136, v137
	v_cvt_pk_bf16_f32 v57, v138, v139
	ds_write_b64 v140, v[56:57] offset:32
	v_pk_mul_f32 v[132:133], v[60:61], s[12:13] op_sel_hi:[1,0]
	v_pk_mul_f32 v[134:135], v[62:63], s[12:13] op_sel_hi:[1,0]
	v_exp_f32_e32 v132, v132
	v_exp_f32_e32 v133, v133
	v_exp_f32_e32 v134, v134
	v_exp_f32_e32 v135, v135
	v_pk_add_f32 v[132:133], v[132:133], 1.0 op_sel_hi:[1,0]
	v_pk_add_f32 v[134:135], v[134:135], 1.0 op_sel_hi:[1,0]
	v_rcp_f32_e32 v136, v132
	v_rcp_f32_e32 v137, v133
	v_rcp_f32_e32 v138, v134
	v_rcp_f32_e32 v139, v135
	v_pk_fma_f32 v[60:61], v[132:133], v[136:137], 1.0 op_sel_hi:[1,1,0] neg_lo:[1,0,0] neg_hi:[1,0,0]
	v_pk_fma_f32 v[62:63], v[134:135], v[138:139], 1.0 op_sel_hi:[1,1,0] neg_lo:[1,0,0] neg_hi:[1,0,0]
	v_pk_fma_f32 v[136:137], v[60:61], v[136:137], v[136:137]
	v_pk_fma_f32 v[138:139], v[62:63], v[138:139], v[138:139]
	v_div_fixup_f32 v136, v136, v132, 1.0
	v_div_fixup_f32 v137, v137, v133, 1.0
	v_div_fixup_f32 v138, v138, v134, 1.0
	v_div_fixup_f32 v139, v139, v135, 1.0
	v_cvt_pk_bf16_f32 v60, v136, v137
	v_cvt_pk_bf16_f32 v61, v138, v139
	ds_write_b64 v140, v[60:61] offset:48
	v_pk_mul_f32 v[132:133], v[16:17], s[12:13] op_sel_hi:[1,0]
	v_pk_mul_f32 v[134:135], v[18:19], s[12:13] op_sel_hi:[1,0]
	v_exp_f32_e32 v132, v132
	v_exp_f32_e32 v133, v133
	v_exp_f32_e32 v134, v134
	v_exp_f32_e32 v135, v135
	v_pk_add_f32 v[132:133], v[132:133], 1.0 op_sel_hi:[1,0]
	v_pk_add_f32 v[134:135], v[134:135], 1.0 op_sel_hi:[1,0]
	v_rcp_f32_e32 v136, v132
	v_rcp_f32_e32 v137, v133
	v_rcp_f32_e32 v138, v134
	v_rcp_f32_e32 v139, v135
	v_pk_fma_f32 v[16:17], v[132:133], v[136:137], 1.0 op_sel_hi:[1,1,0] neg_lo:[1,0,0] neg_hi:[1,0,0]
	v_pk_fma_f32 v[18:19], v[134:135], v[138:139], 1.0 op_sel_hi:[1,1,0] neg_lo:[1,0,0] neg_hi:[1,0,0]
	v_pk_fma_f32 v[136:137], v[16:17], v[136:137], v[136:137]
; DI float sigmoidf_(float x) { return 1.f / (1.f + __expf(-x)); }
; template <int WM>
; DI void inproj_tile(const Params& p, char* smem, const int m0, const int n0) {
;     ...
;   } else if (fw < 4352) {
; #pragma unroll
;     for (int i = 0; i < WM; ++i)
; #pragma unroll
;       for (int j = 0; j < 2; ++j)
; #pragma unroll
;         for (int q4 = 0; q4 < 4; ++q4) {
;           const int f = fw - 2304 + i * 32 + q4 * 8 + hh * 4;
;           const size_t t = tb + j * 32;
;           uint2 o;
;           o.x = pack2(sigmoidf_(acc[i][j][q4 * 4 + 0]), sigmoidf_(acc[i][j][q4 * 4 + 1]));
;           o.y = pack2(sigmoidf_(acc[i][j][q4 * 4 + 2]), sigmoidf_(acc[i][j][q4 * 4 + 3]));
;           *(uint2*)(MG + t * 2048 + f) = o;
;         }
	v_pk_fma_f32 v[138:139], v[18:19], v[138:139], v[138:139]
	v_div_fixup_f32 v136, v136, v132, 1.0
	v_div_fixup_f32 v137, v137, v133, 1.0
	v_div_fixup_f32 v138, v138, v134, 1.0
	v_div_fixup_f32 v139, v139, v135, 1.0
	v_cvt_pk_bf16_f32 v16, v136, v137
	v_cvt_pk_bf16_f32 v17, v138, v139
	ds_write_b64 v140, v[16:17] offset:64
	v_pk_mul_f32 v[132:133], v[20:21], s[12:13] op_sel_hi:[1,0]
	v_pk_mul_f32 v[134:135], v[22:23], s[12:13] op_sel_hi:[1,0]
	v_exp_f32_e32 v132, v132
	v_exp_f32_e32 v133, v133
	v_exp_f32_e32 v134, v134
	v_exp_f32_e32 v135, v135
	v_pk_add_f32 v[132:133], v[132:133], 1.0 op_sel_hi:[1,0]
	v_pk_add_f32 v[134:135], v[134:135], 1.0 op_sel_hi:[1,0]
	v_rcp_f32_e32 v136, v132
	v_rcp_f32_e32 v137, v133
	v_rcp_f32_e32 v138, v134
	v_rcp_f32_e32 v139, v135
	v_pk_fma_f32 v[20:21], v[132:133], v[136:137], 1.0 op_sel_hi:[1,1,0] neg_lo:[1,0,0] neg_hi:[1,0,0]
	v_pk_fma_f32 v[22:23], v[134:135], v[138:139], 1.0 op_sel_hi:[1,1,0] neg_lo:[1,0,0] neg_hi:[1,0,0]
	v_pk_fma_f32 v[136:137], v[20:21], v[136:137], v[136:137]
	v_pk_fma_f32 v[138:139], v[22:23], v[138:139], v[138:139]
	v_div_fixup_f32 v136, v136, v132, 1.0
	v_div_fixup_f32 v137, v137, v133, 1.0
	v_div_fixup_f32 v138, v138, v134, 1.0
	v_div_fixup_f32 v139, v139, v135, 1.0
	v_cvt_pk_bf16_f32 v20, v136, v137
	v_cvt_pk_bf16_f32 v21, v138, v139
	ds_write_b64 v140, v[20:21] offset:80
	v_pk_mul_f32 v[132:133], v[24:25], s[12:13] op_sel_hi:[1,0]
	v_pk_mul_f32 v[134:135], v[26:27], s[12:13] op_sel_hi:[1,0]
	v_exp_f32_e32 v132, v132
	v_exp_f32_e32 v133, v133
	v_exp_f32_e32 v134, v134
	v_exp_f32_e32 v135, v135
	v_pk_add_f32 v[132:133], v[132:133], 1.0 op_sel_hi:[1,0]
	v_pk_add_f32 v[134:135], v[134:135], 1.0 op_sel_hi:[1,0]
	v_rcp_f32_e32 v136, v132
	v_rcp_f32_e32 v137, v133
	v_rcp_f32_e32 v138, v134
	v_rcp_f32_e32 v139, v135
	v_pk_fma_f32 v[24:25], v[132:133], v[136:137], 1.0 op_sel_hi:[1,1,0] neg_lo:[1,0,0] neg_hi:[1,0,0]
	v_pk_fma_f32 v[26:27], v[134:135], v[138:139], 1.0 op_sel_hi:[1,1,0] neg_lo:[1,0,0] neg_hi:[1,0,0]
	v_pk_fma_f32 v[136:137], v[24:25], v[136:137], v[136:137]
	v_pk_fma_f32 v[138:139], v[26:27], v[138:139], v[138:139]
	v_div_fixup_f32 v136, v136, v132, 1.0
	v_div_fixup_f32 v137, v137, v133, 1.0
	v_div_fixup_f32 v138, v138, v134, 1.0
	v_div_fixup_f32 v139, v139, v135, 1.0
	v_cvt_pk_bf16_f32 v24, v136, v137
	v_cvt_pk_bf16_f32 v25, v138, v139
	ds_write_b64 v140, v[24:25] offset:96
	v_pk_mul_f32 v[132:133], v[28:29], s[12:13] op_sel_hi:[1,0]
	v_pk_mul_f32 v[134:135], v[30:31], s[12:13] op_sel_hi:[1,0]
	v_exp_f32_e32 v132, v132
	v_exp_f32_e32 v133, v133
	v_exp_f32_e32 v134, v134
	v_exp_f32_e32 v135, v135
	v_pk_add_f32 v[132:133], v[132:133], 1.0 op_sel_hi:[1,0]
	v_pk_add_f32 v[134:135], v[134:135], 1.0 op_sel_hi:[1,0]
	v_rcp_f32_e32 v136, v132
	v_rcp_f32_e32 v137, v133
	v_rcp_f32_e32 v138, v134
	v_rcp_f32_e32 v139, v135
	v_pk_fma_f32 v[28:29], v[132:133], v[136:137], 1.0 op_sel_hi:[1,1,0] neg_lo:[1,0,0] neg_hi:[1,0,0]
	v_pk_fma_f32 v[30:31], v[134:135], v[138:139], 1.0 op_sel_hi:[1,1,0] neg_lo:[1,0,0] neg_hi:[1,0,0]
	v_pk_fma_f32 v[136:137], v[28:29], v[136:137], v[136:137]
	v_pk_fma_f32 v[138:139], v[30:31], v[138:139], v[138:139]
	v_div_fixup_f32 v136, v136, v132, 1.0
	v_div_fixup_f32 v137, v137, v133, 1.0
	v_div_fixup_f32 v138, v138, v134, 1.0
	v_div_fixup_f32 v139, v139, v135, 1.0
	v_cvt_pk_bf16_f32 v28, v136, v137
	v_cvt_pk_bf16_f32 v29, v138, v139
	ds_write_b64 v140, v[28:29] offset:112
	ds_read_b128 v[144:147], v141 offset:0
	ds_read_b128 v[148:151], v141 offset:1152
	ds_read_b128 v[152:155], v141 offset:2304
	ds_read_b128 v[156:159], v141 offset:3456
	s_waitcnt lgkmcnt(3)
	global_store_dwordx4 v142, v[144:147], s[8:9]
	v_add_u32_e32 v142, 0x8000, v142
	s_waitcnt lgkmcnt(2)
	global_store_dwordx4 v142, v[148:151], s[8:9]
	v_add_u32_e32 v142, 0x8000, v142
	s_waitcnt lgkmcnt(1)
	global_store_dwordx4 v142, v[152:155], s[8:9]
	v_add_u32_e32 v142, 0x8000, v142
	s_waitcnt lgkmcnt(0)
	global_store_dwordx4 v142, v[156:159], s[8:9]
	v_add_u32_e32 v142, 0x8000, v142
	v_pk_mul_f32 v[132:133], v[32:33], s[12:13] op_sel_hi:[1,0]
	v_pk_mul_f32 v[134:135], v[34:35], s[12:13] op_sel_hi:[1,0]
	v_exp_f32_e32 v132, v132
	v_exp_f32_e32 v133, v133
	v_exp_f32_e32 v134, v134
	v_exp_f32_e32 v135, v135
	v_pk_add_f32 v[132:133], v[132:133], 1.0 op_sel_hi:[1,0]
	v_pk_add_f32 v[134:135], v[134:135], 1.0 op_sel_hi:[1,0]
	v_rcp_f32_e32 v136, v132
	v_rcp_f32_e32 v137, v133
	v_rcp_f32_e32 v138, v134
	v_rcp_f32_e32 v139, v135
	v_pk_fma_f32 v[32:33], v[132:133], v[136:137], 1.0 op_sel_hi:[1,1,0] neg_lo:[1,0,0] neg_hi:[1,0,0]
	v_pk_fma_f32 v[34:35], v[134:135], v[138:139], 1.0 op_sel_hi:[1,1,0] neg_lo:[1,0,0] neg_hi:[1,0,0]
	v_pk_fma_f32 v[136:137], v[32:33], v[136:137], v[136:137]
	v_pk_fma_f32 v[138:139], v[34:35], v[138:139], v[138:139]
	v_div_fixup_f32 v136, v136, v132, 1.0
	v_div_fixup_f32 v137, v137, v133, 1.0
	v_div_fixup_f32 v138, v138, v134, 1.0
	v_div_fixup_f32 v139, v139, v135, 1.0
	v_cvt_pk_bf16_f32 v32, v136, v137
	v_cvt_pk_bf16_f32 v33, v138, v139
	ds_write_b64 v140, v[32:33] offset:4608
	v_pk_mul_f32 v[132:133], v[36:37], s[12:13] op_sel_hi:[1,0]
	v_pk_mul_f32 v[134:135], v[38:39], s[12:13] op_sel_hi:[1,0]
	v_exp_f32_e32 v132, v132
	v_exp_f32_e32 v133, v133
	v_exp_f32_e32 v134, v134
	v_exp_f32_e32 v135, v135
	v_pk_add_f32 v[132:133], v[132:133], 1.0 op_sel_hi:[1,0]
	v_pk_add_f32 v[134:135], v[134:135], 1.0 op_sel_hi:[1,0]
	v_rcp_f32_e32 v136, v132
	v_rcp_f32_e32 v137, v133
	v_rcp_f32_e32 v138, v134
	v_rcp_f32_e32 v139, v135
	v_pk_fma_f32 v[36:37], v[132:133], v[136:137], 1.0 op_sel_hi:[1,1,0] neg_lo:[1,0,0] neg_hi:[1,0,0]
	v_pk_fma_f32 v[38:39], v[134:135], v[138:139], 1.0 op_sel_hi:[1,1,0] neg_lo:[1,0,0] neg_hi:[1,0,0]
; DI float sigmoidf_(float x) { return 1.f / (1.f + __expf(-x)); }
; template <int WM>
; DI void inproj_tile(const Params& p, char* smem, const int m0, const int n0) {
;     ...
;   } else if (fw < 4352) {
; #pragma unroll
;     for (int i = 0; i < WM; ++i)
; #pragma unroll
;       for (int j = 0; j < 2; ++j)
; #pragma unroll
;         for (int q4 = 0; q4 < 4; ++q4) {
;           const int f = fw - 2304 + i * 32 + q4 * 8 + hh * 4;
;           const size_t t = tb + j * 32;
;           uint2 o;
;           o.x = pack2(sigmoidf_(acc[i][j][q4 * 4 + 0]), sigmoidf_(acc[i][j][q4 * 4 + 1]));
;           o.y = pack2(sigmoidf_(acc[i][j][q4 * 4 + 2]), sigmoidf_(acc[i][j][q4 * 4 + 3]));
;           *(uint2*)(MG + t * 2048 + f) = o;
;         }
	v_pk_fma_f32 v[136:137], v[36:37], v[136:137], v[136:137]
	v_pk_fma_f32 v[138:139], v[38:39], v[138:139], v[138:139]
	v_div_fixup_f32 v136, v136, v132, 1.0
	v_div_fixup_f32 v137, v137, v133, 1.0
	v_div_fixup_f32 v138, v138, v134, 1.0
	v_div_fixup_f32 v139, v139, v135, 1.0
	v_cvt_pk_bf16_f32 v36, v136, v137
	v_cvt_pk_bf16_f32 v37, v138, v139
	ds_write_b64 v140, v[36:37] offset:4624
	v_pk_mul_f32 v[132:133], v[40:41], s[12:13] op_sel_hi:[1,0]
	v_pk_mul_f32 v[134:135], v[42:43], s[12:13] op_sel_hi:[1,0]
	v_exp_f32_e32 v132, v132
	v_exp_f32_e32 v133, v133
	v_exp_f32_e32 v134, v134
	v_exp_f32_e32 v135, v135
	v_pk_add_f32 v[132:133], v[132:133], 1.0 op_sel_hi:[1,0]
	v_pk_add_f32 v[134:135], v[134:135], 1.0 op_sel_hi:[1,0]
	v_rcp_f32_e32 v136, v132
	v_rcp_f32_e32 v137, v133
	v_rcp_f32_e32 v138, v134
	v_rcp_f32_e32 v139, v135
	v_pk_fma_f32 v[40:41], v[132:133], v[136:137], 1.0 op_sel_hi:[1,1,0] neg_lo:[1,0,0] neg_hi:[1,0,0]
	v_pk_fma_f32 v[42:43], v[134:135], v[138:139], 1.0 op_sel_hi:[1,1,0] neg_lo:[1,0,0] neg_hi:[1,0,0]
	v_pk_fma_f32 v[136:137], v[40:41], v[136:137], v[136:137]
	v_pk_fma_f32 v[138:139], v[42:43], v[138:139], v[138:139]
	v_div_fixup_f32 v136, v136, v132, 1.0
	v_div_fixup_f32 v137, v137, v133, 1.0
	v_div_fixup_f32 v138, v138, v134, 1.0
	v_div_fixup_f32 v139, v139, v135, 1.0
	v_cvt_pk_bf16_f32 v40, v136, v137
	v_cvt_pk_bf16_f32 v41, v138, v139
	ds_write_b64 v140, v[40:41] offset:4640
	v_pk_mul_f32 v[132:133], v[44:45], s[12:13] op_sel_hi:[1,0]
	v_pk_mul_f32 v[134:135], v[46:47], s[12:13] op_sel_hi:[1,0]
	v_exp_f32_e32 v132, v132
	v_exp_f32_e32 v133, v133
	v_exp_f32_e32 v134, v134
	v_exp_f32_e32 v135, v135
	v_pk_add_f32 v[132:133], v[132:133], 1.0 op_sel_hi:[1,0]
	v_pk_add_f32 v[134:135], v[134:135], 1.0 op_sel_hi:[1,0]
	v_rcp_f32_e32 v136, v132
	v_rcp_f32_e32 v137, v133
	v_rcp_f32_e32 v138, v134
	v_rcp_f32_e32 v139, v135
	v_pk_fma_f32 v[44:45], v[132:133], v[136:137], 1.0 op_sel_hi:[1,1,0] neg_lo:[1,0,0] neg_hi:[1,0,0]
	v_pk_fma_f32 v[46:47], v[134:135], v[138:139], 1.0 op_sel_hi:[1,1,0] neg_lo:[1,0,0] neg_hi:[1,0,0]
	v_pk_fma_f32 v[136:137], v[44:45], v[136:137], v[136:137]
	v_pk_fma_f32 v[138:139], v[46:47], v[138:139], v[138:139]
	v_div_fixup_f32 v136, v136, v132, 1.0
	v_div_fixup_f32 v137, v137, v133, 1.0
	v_div_fixup_f32 v138, v138, v134, 1.0
	v_div_fixup_f32 v139, v139, v135, 1.0
	v_cvt_pk_bf16_f32 v44, v136, v137
	v_cvt_pk_bf16_f32 v45, v138, v139
	ds_write_b64 v140, v[44:45] offset:4656
	v_pk_mul_f32 v[132:133], v[0:1], s[12:13] op_sel_hi:[1,0]
	v_pk_mul_f32 v[134:135], v[2:3], s[12:13] op_sel_hi:[1,0]
	v_exp_f32_e32 v132, v132
	v_exp_f32_e32 v133, v133
	v_exp_f32_e32 v134, v134
	v_exp_f32_e32 v135, v135
	v_pk_add_f32 v[132:133], v[132:133], 1.0 op_sel_hi:[1,0]
	v_pk_add_f32 v[134:135], v[134:135], 1.0 op_sel_hi:[1,0]
	v_rcp_f32_e32 v136, v132
	v_rcp_f32_e32 v137, v133
	v_rcp_f32_e32 v138, v134
	v_rcp_f32_e32 v139, v135
	v_pk_fma_f32 v[0:1], v[132:133], v[136:137], 1.0 op_sel_hi:[1,1,0] neg_lo:[1,0,0] neg_hi:[1,0,0]
	v_pk_fma_f32 v[2:3], v[134:135], v[138:139], 1.0 op_sel_hi:[1,1,0] neg_lo:[1,0,0] neg_hi:[1,0,0]
	v_pk_fma_f32 v[136:137], v[0:1], v[136:137], v[136:137]
	v_pk_fma_f32 v[138:139], v[2:3], v[138:139], v[138:139]
	v_div_fixup_f32 v136, v136, v132, 1.0
	v_div_fixup_f32 v137, v137, v133, 1.0
	v_div_fixup_f32 v138, v138, v134, 1.0
	v_div_fixup_f32 v139, v139, v135, 1.0
	v_cvt_pk_bf16_f32 v0, v136, v137
	v_cvt_pk_bf16_f32 v1, v138, v139
	ds_write_b64 v140, v[0:1] offset:4672
	v_pk_mul_f32 v[132:133], v[4:5], s[12:13] op_sel_hi:[1,0]
	v_pk_mul_f32 v[134:135], v[6:7], s[12:13] op_sel_hi:[1,0]
	v_exp_f32_e32 v132, v132
	v_exp_f32_e32 v133, v133
	v_exp_f32_e32 v134, v134
	v_exp_f32_e32 v135, v135
	v_pk_add_f32 v[132:133], v[132:133], 1.0 op_sel_hi:[1,0]
	v_pk_add_f32 v[134:135], v[134:135], 1.0 op_sel_hi:[1,0]
	v_rcp_f32_e32 v136, v132
	v_rcp_f32_e32 v137, v133
	v_rcp_f32_e32 v138, v134
	v_rcp_f32_e32 v139, v135
	v_pk_fma_f32 v[4:5], v[132:133], v[136:137], 1.0 op_sel_hi:[1,1,0] neg_lo:[1,0,0] neg_hi:[1,0,0]
	v_pk_fma_f32 v[6:7], v[134:135], v[138:139], 1.0 op_sel_hi:[1,1,0] neg_lo:[1,0,0] neg_hi:[1,0,0]
	v_pk_fma_f32 v[136:137], v[4:5], v[136:137], v[136:137]
	v_pk_fma_f32 v[138:139], v[6:7], v[138:139], v[138:139]
	v_div_fixup_f32 v136, v136, v132, 1.0
	v_div_fixup_f32 v137, v137, v133, 1.0
	v_div_fixup_f32 v138, v138, v134, 1.0
	v_div_fixup_f32 v139, v139, v135, 1.0
	v_cvt_pk_bf16_f32 v4, v136, v137
	v_cvt_pk_bf16_f32 v5, v138, v139
	ds_write_b64 v140, v[4:5] offset:4688
	v_pk_mul_f32 v[132:133], v[8:9], s[12:13] op_sel_hi:[1,0]
	v_pk_mul_f32 v[134:135], v[10:11], s[12:13] op_sel_hi:[1,0]
	v_exp_f32_e32 v132, v132
	v_exp_f32_e32 v133, v133
	v_exp_f32_e32 v134, v134
	v_exp_f32_e32 v135, v135
	v_pk_add_f32 v[132:133], v[132:133], 1.0 op_sel_hi:[1,0]
	v_pk_add_f32 v[134:135], v[134:135], 1.0 op_sel_hi:[1,0]
	v_rcp_f32_e32 v136, v132
	v_rcp_f32_e32 v137, v133
	v_rcp_f32_e32 v138, v134
	v_rcp_f32_e32 v139, v135
	v_pk_fma_f32 v[8:9], v[132:133], v[136:137], 1.0 op_sel_hi:[1,1,0] neg_lo:[1,0,0] neg_hi:[1,0,0]
	v_pk_fma_f32 v[10:11], v[134:135], v[138:139], 1.0 op_sel_hi:[1,1,0] neg_lo:[1,0,0] neg_hi:[1,0,0]
	v_pk_fma_f32 v[136:137], v[8:9], v[136:137], v[136:137]
	v_pk_fma_f32 v[138:139], v[10:11], v[138:139], v[138:139]
	v_div_fixup_f32 v136, v136, v132, 1.0
	v_div_fixup_f32 v137, v137, v133, 1.0
	v_div_fixup_f32 v138, v138, v134, 1.0
	v_div_fixup_f32 v139, v139, v135, 1.0
	v_cvt_pk_bf16_f32 v8, v136, v137
	v_cvt_pk_bf16_f32 v9, v138, v139
	ds_write_b64 v140, v[8:9] offset:4704
	v_pk_mul_f32 v[132:133], v[12:13], s[12:13] op_sel_hi:[1,0]
	v_pk_mul_f32 v[134:135], v[14:15], s[12:13] op_sel_hi:[1,0]
	v_exp_f32_e32 v132, v132
	v_exp_f32_e32 v133, v133
	v_exp_f32_e32 v134, v134
	v_exp_f32_e32 v135, v135
	v_pk_add_f32 v[132:133], v[132:133], 1.0 op_sel_hi:[1,0]
	v_pk_add_f32 v[134:135], v[134:135], 1.0 op_sel_hi:[1,0]
	v_rcp_f32_e32 v136, v132
	v_rcp_f32_e32 v137, v133
	v_rcp_f32_e32 v138, v134
	v_rcp_f32_e32 v139, v135
	v_pk_fma_f32 v[12:13], v[132:133], v[136:137], 1.0 op_sel_hi:[1,1,0] neg_lo:[1,0,0] neg_hi:[1,0,0]
	v_pk_fma_f32 v[14:15], v[134:135], v[138:139], 1.0 op_sel_hi:[1,1,0] neg_lo:[1,0,0] neg_hi:[1,0,0]
	v_pk_fma_f32 v[136:137], v[12:13], v[136:137], v[136:137]
	v_pk_fma_f32 v[138:139], v[14:15], v[138:139], v[138:139]
	v_div_fixup_f32 v136, v136, v132, 1.0
	v_div_fixup_f32 v137, v137, v133, 1.0
	v_div_fixup_f32 v138, v138, v134, 1.0
	v_div_fixup_f32 v139, v139, v135, 1.0
	v_cvt_pk_bf16_f32 v12, v136, v137
	v_cvt_pk_bf16_f32 v13, v138, v139
	ds_write_b64 v140, v[12:13] offset:4720
	ds_read_b128 v[144:147], v141 offset:4608
	ds_read_b128 v[148:151], v141 offset:5760
	ds_read_b128 v[152:155], v141 offset:6912
	ds_read_b128 v[156:159], v141 offset:8064
	s_waitcnt lgkmcnt(3)
; DI float sigmoidf_(float x) { return 1.f / (1.f + __expf(-x)); }
; template <int WM>
; DI void inproj_tile(const Params& p, char* smem, const int m0, const int n0) {
;     ...
;   } else if (fw < 4352) {
; #pragma unroll
;     for (int i = 0; i < WM; ++i)
; #pragma unroll
;       for (int j = 0; j < 2; ++j)
; #pragma unroll
;         for (int q4 = 0; q4 < 4; ++q4) {
;           const int f = fw - 2304 + i * 32 + q4 * 8 + hh * 4;
;           const size_t t = tb + j * 32;
;           uint2 o;
;           o.x = pack2(sigmoidf_(acc[i][j][q4 * 4 + 0]), sigmoidf_(acc[i][j][q4 * 4 + 1]));
;           o.y = pack2(sigmoidf_(acc[i][j][q4 * 4 + 2]), sigmoidf_(acc[i][j][q4 * 4 + 3]));
;           *(uint2*)(MG + t * 2048 + f) = o;
;         }
	global_store_dwordx4 v142, v[144:147], s[8:9]
	v_add_u32_e32 v142, 0x8000, v142
	s_waitcnt lgkmcnt(2)
	global_store_dwordx4 v142, v[148:151], s[8:9]
	v_add_u32_e32 v142, 0x8000, v142
	s_waitcnt lgkmcnt(1)
	global_store_dwordx4 v142, v[152:155], s[8:9]
	v_add_u32_e32 v142, 0x8000, v142
	s_waitcnt lgkmcnt(0)
	global_store_dwordx4 v142, v[156:159], s[8:9]
	v_add_u32_e32 v142, 0x8000, v142
